# GEMM K-loops: A[0][0] stage (2 LDS-DMA) moved from the 6-DMA load segment to the following 2-DMA segment, vmcnt 8->6 there
# speedup vs baseline: 1.0160x; 1.0001x over previous
; #define PG8_STAGE(bufoff, gbase, voff) do { _Pragma("unroll") for (int _i = 0; _i < 2; ++_i) \
;         __builtin_amdgcn_global_load_lds((const unsigned*)((const char*)(gbase) + (voff)[_i]), (PG8_LAS unsigned*)(lds + (bufoff) + ldsw + _i * 8192), 16, 0, 0); } while (0)
; #define PG8_LDA(dst, b, h) do { _Pragma("unroll") for (int m = 0; m < 4; ++m) _Pragma("unroll") for (int k = 0; k < 2; ++k) dst[m][k] = *(const PG8_LAS bf16x8*)(lds + PG8_SA(b, h) + aoff + m * 2048 + k * 1024); } while (0)
; #define PG8_LDB(dst, b, h) do { _Pragma("unroll") for (int n = 0; n < 2; ++n) _Pragma("unroll") for (int k = 0; k < 2; ++k) dst[n][k] = *(const PG8_LAS bf16x8*)(lds + PG8_SB(b, h) + boff + n * 2048 + k * 1024); } while (0)
; #define PG8_MMA(ai, bj, At, Bt) do { __builtin_amdgcn_s_setprio(1); _Pragma("unroll") for (int m = 0; m < 4; ++m) _Pragma("unroll") for (int n = 0; n < 2; ++n) _Pragma("unroll") for (int k = 0; k < 2; ++k) \
;         acc[ai][bj][m][n] = __builtin_amdgcn_mfma_f32_16x16x32_bf16(Bt[n][k], At[m][k], acc[ai][bj][m][n], 0, 0, 0); __builtin_amdgcn_s_setprio(0); } while (0)
; #define PG8_WAIT_V(n) asm volatile("s_waitcnt vmcnt(" #n ")" ::: "memory")
; #define PG8_WAIT_L(n) asm volatile("s_waitcnt lgkmcnt(" #n ")" ::: "memory")
; #define PG8_BAR __builtin_amdgcn_s_barrier()
; #define PG8_SCHED __builtin_amdgcn_sched_barrier(0)
; template <class Epi, class Sched, bool ALIGN_EPI = false, bool SP2 = false>
; __device__ __forceinline__ void gemm_phase(PG8_LAS unsigned char* lds, const Gemm g, const Sched& S, const Epi& E) {
;     ...
;             PG8_LDB(B0, 0, 0); PG8_LDB(B1, 0, 1); PG8_SCHED; PG8_LDA(At, 0, 0); PG8_STAGE(PG8_SA(1, 1), a1 + hstep, voffA);
;             PG8_WAIT_V(8); PG8_WAIT_L(0); PG8_BAR; PG8_MMA(0, 0, At, B0); PG8_MMA(0, 1, At, B1); PG8_BAR; PG8_SCHED;
;             PG8_LDA(At, 0, 1); PG8_STAGE(PG8_SB(0, 0), b2, voffB); PG8_STAGE(PG8_SB(0, 1), b2 + hstep, voffB); PG8_STAGE(PG8_SA(0, 0), a2, voffA);
;             PG8_WAIT_V(8); PG8_WAIT_L(0); PG8_BAR; PG8_MMA(1, 0, At, B0); PG8_MMA(1, 1, At, B1); PG8_BAR; PG8_SCHED;
.LBB0_146:
	ds_read_b128 v[150:153], v156
	ds_read_b128 v[162:165], v156 offset:1024
	ds_read_b128 v[166:169], v156 offset:2048
	ds_read_b128 v[170:173], v156 offset:3072
	ds_read_b128 v[174:177], v157
	ds_read_b128 v[178:181], v157 offset:1024
	ds_read_b128 v[182:185], v157 offset:2048
	ds_read_b128 v[186:189], v157 offset:3072
	s_add_u32 s36, s34, 0xfffc0080
	s_addc_u32 s37, s35, -1
	s_cmp_eq_u32 s89, 12
	s_cselect_b32 s39, s25, s37
	s_cselect_b32 s38, s31, s36
	s_cselect_b32 s37, s23, s88
	s_cselect_b32 s36, s86, s87
	v_lshl_add_u64 v[222:223], s[34:35], 0, v[140:141]
	s_add_i32 m0, s49, 0xc000
	ds_read_b128 v[190:193], v158
	ds_read_b128 v[194:197], v158 offset:1024
	ds_read_b128 v[198:201], v158 offset:2048
	ds_read_b128 v[202:205], v158 offset:3072
	ds_read_b128 v[206:209], v158 offset:4096
	ds_read_b128 v[210:213], v158 offset:5120
	ds_read_b128 v[214:217], v158 offset:6144
	ds_read_b128 v[218:221], v158 offset:7168
	global_load_lds_dwordx4 v[222:223], off
	v_lshl_add_u64 v[222:223], s[34:35], 0, v[142:143]
	s_add_i32 m0, s49, 0xe000
	s_nop 0
	global_load_lds_dwordx4 v[222:223], off
	s_waitcnt vmcnt(8)
	s_waitcnt lgkmcnt(0)
	s_barrier
	s_setprio 1
	s_waitcnt lgkmcnt(0)
	v_mfma_f32_16x16x32_bf16 v[124:127], v[150:153], v[190:193], v[124:127]
	v_mfma_f32_16x16x32_bf16 v[120:123], v[166:169], v[190:193], v[120:123]
	v_mfma_f32_16x16x32_bf16 v[108:111], v[150:153], v[198:201], v[108:111]
	v_mfma_f32_16x16x32_bf16 v[104:107], v[166:169], v[198:201], v[104:107]
	v_mfma_f32_16x16x32_bf16 v[92:95], v[150:153], v[206:209], v[92:95]
	v_mfma_f32_16x16x32_bf16 v[88:91], v[166:169], v[206:209], v[88:91]
	v_mfma_f32_16x16x32_bf16 v[76:79], v[150:153], v[214:217], v[76:79]
	v_mfma_f32_16x16x32_bf16 v[72:75], v[166:169], v[214:217], v[72:75]
	v_mfma_f32_16x16x32_bf16 v[124:127], v[162:165], v[194:197], v[124:127]
	v_mfma_f32_16x16x32_bf16 v[120:123], v[170:173], v[194:197], v[120:123]
	v_mfma_f32_16x16x32_bf16 v[108:111], v[162:165], v[202:205], v[108:111]
	v_mfma_f32_16x16x32_bf16 v[104:107], v[170:173], v[202:205], v[104:107]
	v_mfma_f32_16x16x32_bf16 v[92:95], v[162:165], v[210:213], v[92:95]
	v_mfma_f32_16x16x32_bf16 v[88:91], v[170:173], v[210:213], v[88:91]
	v_mfma_f32_16x16x32_bf16 v[76:79], v[162:165], v[218:221], v[76:79]
	v_mfma_f32_16x16x32_bf16 v[72:75], v[170:173], v[218:221], v[72:75]
	s_setprio 0
	s_setprio 1
	v_mfma_f32_16x16x32_bf16 v[116:119], v[174:177], v[190:193], v[116:119]
	v_mfma_f32_16x16x32_bf16 v[112:115], v[182:185], v[190:193], v[112:115]
	v_mfma_f32_16x16x32_bf16 v[100:103], v[174:177], v[198:201], v[100:103]
	v_mfma_f32_16x16x32_bf16 v[96:99], v[182:185], v[198:201], v[96:99]
	v_mfma_f32_16x16x32_bf16 v[84:87], v[174:177], v[206:209], v[84:87]
	v_mfma_f32_16x16x32_bf16 v[80:83], v[182:185], v[206:209], v[80:83]
	v_mfma_f32_16x16x32_bf16 v[68:71], v[174:177], v[214:217], v[68:71]
	v_mfma_f32_16x16x32_bf16 v[64:67], v[182:185], v[214:217], v[64:67]
	v_mfma_f32_16x16x32_bf16 v[116:119], v[178:181], v[194:197], v[116:119]
	v_mfma_f32_16x16x32_bf16 v[112:115], v[186:189], v[194:197], v[112:115]
	v_mfma_f32_16x16x32_bf16 v[100:103], v[178:181], v[202:205], v[100:103]
	v_mfma_f32_16x16x32_bf16 v[96:99], v[186:189], v[202:205], v[96:99]
	v_mfma_f32_16x16x32_bf16 v[84:87], v[178:181], v[210:213], v[84:87]
	v_mfma_f32_16x16x32_bf16 v[80:83], v[186:189], v[210:213], v[80:83]
	v_mfma_f32_16x16x32_bf16 v[68:71], v[178:181], v[218:221], v[68:71]
	v_mfma_f32_16x16x32_bf16 v[64:67], v[186:189], v[218:221], v[64:67]
	s_setprio 0
	s_barrier
	s_add_i32 s90, s66, s41
	v_lshl_add_u64 v[222:223], s[36:37], 0, v[134:135]
	s_mov_b32 m0, s90
	ds_read_b128 v[190:193], v158 offset:16384
	ds_read_b128 v[194:197], v158 offset:17408
	ds_read_b128 v[198:201], v158 offset:18432
	ds_read_b128 v[202:205], v158 offset:19456
	ds_read_b128 v[206:209], v158 offset:20480
	ds_read_b128 v[210:213], v158 offset:21504
	ds_read_b128 v[214:217], v158 offset:22528
	ds_read_b128 v[218:221], v158 offset:23552
	global_load_lds_dwordx4 v[222:223], off
	s_add_i32 m0, s90, 0x2000
	s_add_u32 s90, s36, 0x40000
	v_lshl_add_u64 v[224:225], s[36:37], 0, v[130:131]
	s_addc_u32 s91, s37, 0
	s_add_i32 s92, s67, s41
	global_load_lds_dwordx4 v[224:225], off
	v_lshl_add_u64 v[226:227], s[90:91], 0, v[134:135]
	s_mov_b32 m0, s92
	s_nop 0
	global_load_lds_dwordx4 v[226:227], off
	v_lshl_add_u64 v[226:227], s[90:91], 0, v[130:131]
	s_add_i32 m0, s92, 0x2000
	s_nop 0
	global_load_lds_dwordx4 v[226:227], off
	s_nop 0
	s_waitcnt vmcnt(6)
	s_waitcnt lgkmcnt(0)
	s_barrier
; #define PG8_STAGE(bufoff, gbase, voff) do { _Pragma("unroll") for (int _i = 0; _i < 2; ++_i) \
;         __builtin_amdgcn_global_load_lds((const unsigned*)((const char*)(gbase) + (voff)[_i]), (PG8_LAS unsigned*)(lds + (bufoff) + ldsw + _i * 8192), 16, 0, 0); } while (0)
; #define PG8_LDA(dst, b, h) do { _Pragma("unroll") for (int m = 0; m < 4; ++m) _Pragma("unroll") for (int k = 0; k < 2; ++k) dst[m][k] = *(const PG8_LAS bf16x8*)(lds + PG8_SA(b, h) + aoff + m * 2048 + k * 1024); } while (0)
; #define PG8_LDB(dst, b, h) do { _Pragma("unroll") for (int n = 0; n < 2; ++n) _Pragma("unroll") for (int k = 0; k < 2; ++k) dst[n][k] = *(const PG8_LAS bf16x8*)(lds + PG8_SB(b, h) + boff + n * 2048 + k * 1024); } while (0)
; #define PG8_MMA(ai, bj, At, Bt) do { __builtin_amdgcn_s_setprio(1); _Pragma("unroll") for (int m = 0; m < 4; ++m) _Pragma("unroll") for (int n = 0; n < 2; ++n) _Pragma("unroll") for (int k = 0; k < 2; ++k) \
;         acc[ai][bj][m][n] = __builtin_amdgcn_mfma_f32_16x16x32_bf16(Bt[n][k], At[m][k], acc[ai][bj][m][n], 0, 0, 0); __builtin_amdgcn_s_setprio(0); } while (0)
; #define PG8_WAIT_V(n) asm volatile("s_waitcnt vmcnt(" #n ")" ::: "memory")
; #define PG8_WAIT_L(n) asm volatile("s_waitcnt lgkmcnt(" #n ")" ::: "memory")
; #define PG8_BAR __builtin_amdgcn_s_barrier()
; #define PG8_SCHED __builtin_amdgcn_sched_barrier(0)
; template <class Epi, class Sched, bool ALIGN_EPI = false, bool SP2 = false>
; __device__ __forceinline__ void gemm_phase(PG8_LAS unsigned char* lds, const Gemm g, const Sched& S, const Epi& E) {
;     ...
;             PG8_WAIT_V(8); PG8_WAIT_L(0); PG8_BAR; PG8_MMA(1, 0, At, B0); PG8_MMA(1, 1, At, B1); PG8_BAR; PG8_SCHED;
;             PG8_LDB(B0, 1, 0); PG8_LDB(B1, 1, 1); PG8_SCHED; PG8_LDA(At, 1, 0); PG8_STAGE(PG8_SA(0, 1), a2 + hstep, voffA);
;             PG8_WAIT_V(8); PG8_WAIT_L(0); PG8_BAR; PG8_MMA(0, 0, At, B0); PG8_MMA(0, 1, At, B1); PG8_BAR; PG8_SCHED;
;             PG8_LDA(At, 1, 1); PG8_STAGE(PG8_SB(1, 0), b3, voffB); PG8_STAGE(PG8_SB(1, 1), b3 + hstep, voffB); PG8_STAGE(PG8_SA(1, 0), a3, voffA);
;             PG8_WAIT_V(8); PG8_WAIT_L(0); PG8_BAR; PG8_MMA(1, 0, At, B0); PG8_MMA(1, 1, At, B1); PG8_BAR; PG8_SCHED;
	s_setprio 1
	s_waitcnt lgkmcnt(0)
	v_mfma_f32_16x16x32_bf16 v[60:63], v[150:153], v[190:193], v[60:63]
	v_mfma_f32_16x16x32_bf16 v[56:59], v[166:169], v[190:193], v[56:59]
	v_mfma_f32_16x16x32_bf16 v[44:47], v[150:153], v[198:201], v[44:47]
	v_mfma_f32_16x16x32_bf16 v[40:43], v[166:169], v[198:201], v[40:43]
	v_mfma_f32_16x16x32_bf16 v[28:31], v[150:153], v[206:209], v[28:31]
	v_mfma_f32_16x16x32_bf16 v[24:27], v[166:169], v[206:209], v[24:27]
	v_mfma_f32_16x16x32_bf16 v[12:15], v[150:153], v[214:217], v[12:15]
	v_mfma_f32_16x16x32_bf16 v[8:11], v[166:169], v[214:217], v[8:11]
	v_mfma_f32_16x16x32_bf16 v[60:63], v[162:165], v[194:197], v[60:63]
	v_mfma_f32_16x16x32_bf16 v[56:59], v[170:173], v[194:197], v[56:59]
	v_mfma_f32_16x16x32_bf16 v[44:47], v[162:165], v[202:205], v[44:47]
	v_mfma_f32_16x16x32_bf16 v[40:43], v[170:173], v[202:205], v[40:43]
	v_mfma_f32_16x16x32_bf16 v[28:31], v[162:165], v[210:213], v[28:31]
	v_mfma_f32_16x16x32_bf16 v[24:27], v[170:173], v[210:213], v[24:27]
	v_mfma_f32_16x16x32_bf16 v[12:15], v[162:165], v[218:221], v[12:15]
	v_mfma_f32_16x16x32_bf16 v[8:11], v[170:173], v[218:221], v[8:11]
	s_setprio 0
	s_setprio 1
	v_mfma_f32_16x16x32_bf16 v[52:55], v[174:177], v[190:193], v[52:55]
	v_mfma_f32_16x16x32_bf16 v[48:51], v[182:185], v[190:193], v[48:51]
	v_mfma_f32_16x16x32_bf16 v[36:39], v[174:177], v[198:201], v[36:39]
	v_mfma_f32_16x16x32_bf16 v[32:35], v[182:185], v[198:201], v[32:35]
	v_mfma_f32_16x16x32_bf16 v[20:23], v[174:177], v[206:209], v[20:23]
	v_mfma_f32_16x16x32_bf16 v[16:19], v[182:185], v[206:209], v[16:19]
	v_mfma_f32_16x16x32_bf16 v[4:7], v[174:177], v[214:217], v[4:7]
	v_mfma_f32_16x16x32_bf16 v[0:3], v[182:185], v[214:217], v[0:3]
	v_mfma_f32_16x16x32_bf16 v[52:55], v[178:181], v[194:197], v[52:55]
	v_mfma_f32_16x16x32_bf16 v[48:51], v[186:189], v[194:197], v[48:51]
	v_mfma_f32_16x16x32_bf16 v[36:39], v[178:181], v[202:205], v[36:39]
	v_mfma_f32_16x16x32_bf16 v[32:35], v[186:189], v[202:205], v[32:35]
	v_mfma_f32_16x16x32_bf16 v[20:23], v[178:181], v[210:213], v[20:23]
	v_mfma_f32_16x16x32_bf16 v[16:19], v[186:189], v[210:213], v[16:19]
	v_mfma_f32_16x16x32_bf16 v[4:7], v[178:181], v[218:221], v[4:7]
	v_mfma_f32_16x16x32_bf16 v[0:3], v[186:189], v[218:221], v[0:3]
	s_setprio 0
	s_barrier
	s_add_i32 s90, 0, 0x18000
	v_add_u32_e32 v138, s90, v154
	s_add_i32 s91, 0, 0x1c000
	ds_read_b128 v[150:153], v138
	ds_read_b128 v[162:165], v138 offset:1024
	ds_read_b128 v[166:169], v138 offset:2048
	ds_read_b128 v[170:173], v138 offset:3072
	v_add_u32_e32 v138, s91, v154
	ds_read_b128 v[174:177], v138
	ds_read_b128 v[178:181], v138 offset:1024
	ds_read_b128 v[182:185], v138 offset:2048
	ds_read_b128 v[186:189], v138 offset:3072
	v_lshl_add_u64 v[228:229], s[38:39], 0, v[132:133]
	v_lshl_add_u64 v[226:227], s[38:39], 0, v[136:137]
	s_mov_b32 m0, s49
	s_nop 0
	global_load_lds_dwordx4 v[226:227], off
	s_mov_b32 m0, s50
	s_nop 0
	global_load_lds_dwordx4 v[228:229], off
	s_add_u32 s38, s38, 0x40000
	s_addc_u32 s39, s39, 0
	s_mov_b32 m0, s51
	v_lshl_add_u64 v[230:231], s[38:39], 0, v[136:137]
	ds_read_b128 v[190:193], v158 offset:32768
	ds_read_b128 v[194:197], v158 offset:33792
	ds_read_b128 v[198:201], v158 offset:34816
	ds_read_b128 v[202:205], v158 offset:35840
	ds_read_b128 v[206:209], v158 offset:36864
	ds_read_b128 v[210:213], v158 offset:37888
	ds_read_b128 v[214:217], v158 offset:38912
	ds_read_b128 v[218:221], v158 offset:39936
	global_load_lds_dwordx4 v[230:231], off
	v_lshl_add_u64 v[230:231], s[38:39], 0, v[132:133]
	s_mov_b32 m0, s52
	s_nop 0
	global_load_lds_dwordx4 v[230:231], off
	s_waitcnt vmcnt(8)
	s_waitcnt lgkmcnt(0)
	s_barrier
	s_setprio 1
	s_waitcnt lgkmcnt(0)
	v_mfma_f32_16x16x32_bf16 v[124:127], v[150:153], v[190:193], v[124:127]
	v_mfma_f32_16x16x32_bf16 v[120:123], v[166:169], v[190:193], v[120:123]
	v_mfma_f32_16x16x32_bf16 v[108:111], v[150:153], v[198:201], v[108:111]
	v_mfma_f32_16x16x32_bf16 v[104:107], v[166:169], v[198:201], v[104:107]
	v_mfma_f32_16x16x32_bf16 v[92:95], v[150:153], v[206:209], v[92:95]
	v_mfma_f32_16x16x32_bf16 v[88:91], v[166:169], v[206:209], v[88:91]
	v_mfma_f32_16x16x32_bf16 v[76:79], v[150:153], v[214:217], v[76:79]
	v_mfma_f32_16x16x32_bf16 v[72:75], v[166:169], v[214:217], v[72:75]
	v_mfma_f32_16x16x32_bf16 v[124:127], v[162:165], v[194:197], v[124:127]
	v_mfma_f32_16x16x32_bf16 v[120:123], v[170:173], v[194:197], v[120:123]
	v_mfma_f32_16x16x32_bf16 v[108:111], v[162:165], v[202:205], v[108:111]
	v_mfma_f32_16x16x32_bf16 v[104:107], v[170:173], v[202:205], v[104:107]
	v_mfma_f32_16x16x32_bf16 v[92:95], v[162:165], v[210:213], v[92:95]
	v_mfma_f32_16x16x32_bf16 v[88:91], v[170:173], v[210:213], v[88:91]
	v_mfma_f32_16x16x32_bf16 v[76:79], v[162:165], v[218:221], v[76:79]
	v_mfma_f32_16x16x32_bf16 v[72:75], v[170:173], v[218:221], v[72:75]
	s_setprio 0
	s_setprio 1
	v_mfma_f32_16x16x32_bf16 v[116:119], v[174:177], v[190:193], v[116:119]
	v_mfma_f32_16x16x32_bf16 v[112:115], v[182:185], v[190:193], v[112:115]
	v_mfma_f32_16x16x32_bf16 v[100:103], v[174:177], v[198:201], v[100:103]
	v_mfma_f32_16x16x32_bf16 v[96:99], v[182:185], v[198:201], v[96:99]
	v_mfma_f32_16x16x32_bf16 v[84:87], v[174:177], v[206:209], v[84:87]
	v_mfma_f32_16x16x32_bf16 v[80:83], v[182:185], v[206:209], v[80:83]
	v_mfma_f32_16x16x32_bf16 v[68:71], v[174:177], v[214:217], v[68:71]
	v_mfma_f32_16x16x32_bf16 v[64:67], v[182:185], v[214:217], v[64:67]
	v_mfma_f32_16x16x32_bf16 v[116:119], v[178:181], v[194:197], v[116:119]
	v_mfma_f32_16x16x32_bf16 v[112:115], v[186:189], v[194:197], v[112:115]
	v_mfma_f32_16x16x32_bf16 v[100:103], v[178:181], v[202:205], v[100:103]
	v_mfma_f32_16x16x32_bf16 v[96:99], v[186:189], v[202:205], v[96:99]
	v_mfma_f32_16x16x32_bf16 v[84:87], v[178:181], v[210:213], v[84:87]
	v_mfma_f32_16x16x32_bf16 v[80:83], v[186:189], v[210:213], v[80:83]
	v_mfma_f32_16x16x32_bf16 v[68:71], v[178:181], v[218:221], v[68:71]
	v_mfma_f32_16x16x32_bf16 v[64:67], v[186:189], v[218:221], v[64:67]
	s_setprio 0
	s_barrier
; #define PG8_STAGE(bufoff, gbase, voff) do { _Pragma("unroll") for (int _i = 0; _i < 2; ++_i) \
;         __builtin_amdgcn_global_load_lds((const unsigned*)((const char*)(gbase) + (voff)[_i]), (PG8_LAS unsigned*)(lds + (bufoff) + ldsw + _i * 8192), 16, 0, 0); } while (0)
; #define PG8_LDA(dst, b, h) do { _Pragma("unroll") for (int m = 0; m < 4; ++m) _Pragma("unroll") for (int k = 0; k < 2; ++k) dst[m][k] = *(const PG8_LAS bf16x8*)(lds + PG8_SA(b, h) + aoff + m * 2048 + k * 1024); } while (0)
; #define PG8_MMA(ai, bj, At, Bt) do { __builtin_amdgcn_s_setprio(1); _Pragma("unroll") for (int m = 0; m < 4; ++m) _Pragma("unroll") for (int n = 0; n < 2; ++n) _Pragma("unroll") for (int k = 0; k < 2; ++k) \
;         acc[ai][bj][m][n] = __builtin_amdgcn_mfma_f32_16x16x32_bf16(Bt[n][k], At[m][k], acc[ai][bj][m][n], 0, 0, 0); __builtin_amdgcn_s_setprio(0); } while (0)
; #define PG8_WAIT_V(n) asm volatile("s_waitcnt vmcnt(" #n ")" ::: "memory")
; #define PG8_WAIT_L(n) asm volatile("s_waitcnt lgkmcnt(" #n ")" ::: "memory")
; #define PG8_BAR __builtin_amdgcn_s_barrier()
; #define PG8_SCHED __builtin_amdgcn_sched_barrier(0)
; template <class Epi, class Sched, bool ALIGN_EPI = false, bool SP2 = false>
; __device__ __forceinline__ void gemm_phase(PG8_LAS unsigned char* lds, const Gemm g, const Sched& S, const Epi& E) {
;     ...
;             PG8_LDA(At, 1, 1); PG8_STAGE(PG8_SB(1, 0), b3, voffB); PG8_STAGE(PG8_SB(1, 1), b3 + hstep, voffB); PG8_STAGE(PG8_SA(1, 0), a3, voffA);
;             PG8_WAIT_V(8); PG8_WAIT_L(0); PG8_BAR; PG8_MMA(1, 0, At, B0); PG8_MMA(1, 1, At, B1); PG8_BAR; PG8_SCHED;
	s_add_i32 s38, s90, s41
	v_lshl_add_u64 v[222:223], v[222:223], 0, s[8:9]
	s_mov_b32 m0, s38
	ds_read_b128 v[190:193], v158 offset:49152
	ds_read_b128 v[194:197], v158 offset:50176
	ds_read_b128 v[198:201], v158 offset:51200
	ds_read_b128 v[202:205], v158 offset:52224
	ds_read_b128 v[206:209], v158 offset:53248
	ds_read_b128 v[210:213], v158 offset:54272
	ds_read_b128 v[214:217], v158 offset:55296
	ds_read_b128 v[218:221], v158 offset:56320
	global_load_lds_dwordx4 v[222:223], off
	s_add_i32 m0, s38, 0x2000
	s_add_u32 s36, s36, 0x40080
	v_lshl_add_u64 v[222:223], v[224:225], 0, s[8:9]
	s_addc_u32 s37, s37, 0
	s_add_i32 s38, s91, s41
	global_load_lds_dwordx4 v[222:223], off
	v_lshl_add_u64 v[222:223], s[36:37], 0, v[134:135]
	s_mov_b32 m0, s38
	s_nop 0
	global_load_lds_dwordx4 v[222:223], off
	v_lshl_add_u64 v[222:223], s[36:37], 0, v[130:131]
	s_add_i32 m0, s38, 0x2000
	s_nop 0
	global_load_lds_dwordx4 v[222:223], off
	v_lshl_add_u64 v[222:223], v[226:227], 0, s[8:9]
	s_mov_b32 m0, s55
	s_nop 0
	global_load_lds_dwordx4 v[222:223], off
	v_lshl_add_u64 v[222:223], v[228:229], 0, s[8:9]
	s_mov_b32 m0, s62
	s_nop 0
	global_load_lds_dwordx4 v[222:223], off
	s_waitcnt vmcnt(8)
	s_waitcnt lgkmcnt(0)
	s_barrier
	s_setprio 1
	s_waitcnt lgkmcnt(0)
	v_mfma_f32_16x16x32_bf16 v[60:63], v[150:153], v[190:193], v[60:63]
	v_mfma_f32_16x16x32_bf16 v[56:59], v[166:169], v[190:193], v[56:59]
	v_mfma_f32_16x16x32_bf16 v[44:47], v[150:153], v[198:201], v[44:47]
	v_mfma_f32_16x16x32_bf16 v[40:43], v[166:169], v[198:201], v[40:43]
	v_mfma_f32_16x16x32_bf16 v[28:31], v[150:153], v[206:209], v[28:31]
	v_mfma_f32_16x16x32_bf16 v[24:27], v[166:169], v[206:209], v[24:27]
	v_mfma_f32_16x16x32_bf16 v[12:15], v[150:153], v[214:217], v[12:15]
	v_mfma_f32_16x16x32_bf16 v[8:11], v[166:169], v[214:217], v[8:11]
	v_mfma_f32_16x16x32_bf16 v[60:63], v[162:165], v[194:197], v[60:63]
	v_mfma_f32_16x16x32_bf16 v[56:59], v[170:173], v[194:197], v[56:59]
	v_mfma_f32_16x16x32_bf16 v[44:47], v[162:165], v[202:205], v[44:47]
	v_mfma_f32_16x16x32_bf16 v[40:43], v[170:173], v[202:205], v[40:43]
	v_mfma_f32_16x16x32_bf16 v[28:31], v[162:165], v[210:213], v[28:31]
	v_mfma_f32_16x16x32_bf16 v[24:27], v[170:173], v[210:213], v[24:27]
	v_mfma_f32_16x16x32_bf16 v[12:15], v[162:165], v[218:221], v[12:15]
	v_mfma_f32_16x16x32_bf16 v[8:11], v[170:173], v[218:221], v[8:11]
	s_setprio 0
	s_setprio 1
	v_mfma_f32_16x16x32_bf16 v[52:55], v[174:177], v[190:193], v[52:55]
	v_mfma_f32_16x16x32_bf16 v[48:51], v[182:185], v[190:193], v[48:51]
	v_mfma_f32_16x16x32_bf16 v[36:39], v[174:177], v[198:201], v[36:39]
	v_mfma_f32_16x16x32_bf16 v[32:35], v[182:185], v[198:201], v[32:35]
	v_mfma_f32_16x16x32_bf16 v[20:23], v[174:177], v[206:209], v[20:23]
	v_mfma_f32_16x16x32_bf16 v[16:19], v[182:185], v[206:209], v[16:19]
	v_mfma_f32_16x16x32_bf16 v[4:7], v[174:177], v[214:217], v[4:7]
	v_mfma_f32_16x16x32_bf16 v[0:3], v[182:185], v[214:217], v[0:3]
	v_mfma_f32_16x16x32_bf16 v[52:55], v[178:181], v[194:197], v[52:55]
	v_mfma_f32_16x16x32_bf16 v[48:51], v[186:189], v[194:197], v[48:51]
	v_mfma_f32_16x16x32_bf16 v[36:39], v[178:181], v[202:205], v[36:39]
	v_mfma_f32_16x16x32_bf16 v[32:35], v[186:189], v[202:205], v[32:35]
	v_mfma_f32_16x16x32_bf16 v[20:23], v[178:181], v[210:213], v[20:23]
	v_mfma_f32_16x16x32_bf16 v[16:19], v[186:189], v[210:213], v[16:19]
	v_mfma_f32_16x16x32_bf16 v[4:7], v[178:181], v[218:221], v[4:7]
	v_mfma_f32_16x16x32_bf16 v[0:3], v[186:189], v[218:221], v[0:3]
	s_setprio 0
	s_barrier
	s_add_i32 s89, s89, 2
	s_add_u32 s34, s34, 0x100
	s_addc_u32 s35, s35, 0
	s_add_u32 s87, s87, 0x100
	s_addc_u32 s88, s88, 0
	s_cmp_gt_u32 s89, 13
	s_cbranch_scc0 .LBB0_146
	s_and_b64 vcc, exec, s[10:11]
	s_cbranch_vccnz .LBB0_151
	v_lshl_add_u32 v150, s30, 8, v129
	s_cmp_lt_i32 s3, 12
	s_mov_b64 s[30:31], -1
	s_cbranch_scc1 .LBB0_152

; #define PG8_STAGE(bufoff, gbase, voff) do { _Pragma("unroll") for (int _i = 0; _i < 2; ++_i) \
;         __builtin_amdgcn_global_load_lds((const unsigned*)((const char*)(gbase) + (voff)[_i]), (PG8_LAS unsigned*)(lds + (bufoff) + ldsw + _i * 8192), 16, 0, 0); } while (0)
; #define PG8_LDA(dst, b, h) do { _Pragma("unroll") for (int m = 0; m < 4; ++m) _Pragma("unroll") for (int k = 0; k < 2; ++k) dst[m][k] = *(const PG8_LAS bf16x8*)(lds + PG8_SA(b, h) + aoff + m * 2048 + k * 1024); } while (0)
; #define PG8_LDB(dst, b, h) do { _Pragma("unroll") for (int n = 0; n < 2; ++n) _Pragma("unroll") for (int k = 0; k < 2; ++k) dst[n][k] = *(const PG8_LAS bf16x8*)(lds + PG8_SB(b, h) + boff + n * 2048 + k * 1024); } while (0)
; #define PG8_MMA(ai, bj, At, Bt) do { __builtin_amdgcn_s_setprio(1); _Pragma("unroll") for (int m = 0; m < 4; ++m) _Pragma("unroll") for (int n = 0; n < 2; ++n) _Pragma("unroll") for (int k = 0; k < 2; ++k) \
;         acc[ai][bj][m][n] = __builtin_amdgcn_mfma_f32_16x16x32_bf16(Bt[n][k], At[m][k], acc[ai][bj][m][n], 0, 0, 0); __builtin_amdgcn_s_setprio(0); } while (0)
; #define PG8_WAIT_V(n) asm volatile("s_waitcnt vmcnt(" #n ")" ::: "memory")
; #define PG8_WAIT_L(n) asm volatile("s_waitcnt lgkmcnt(" #n ")" ::: "memory")
; template <class Epi, class Sched, bool ALIGN_EPI = false, bool SP2 = false>
; __device__ __forceinline__ void gemm_phase(PG8_LAS unsigned char* lds, const Gemm g, const Sched& S, const Epi& E) {
;     ...
;             const bool last = (t == nt - 2);
;             const char* a1 = cA + (size_t)(t + 1) * kstep;
;             const char* a2 = last ? nA : cA + (size_t)(t + 2) * kstep; const char* b2 = last ? nB : cB + (size_t)(t + 2) * kstep;
;             const char* a3 = a2 + kstep; const char* b3 = b2 + kstep;
;             if (last && has_next) S.a_ready(nxt);
;             if constexpr (SP2) {
;             PG8_LDB(B0, 0, 0); PG8_LDB(B1, 0, 1); PG8_SCHED; PG8_LDA(At, 0, 0); PG8_STAGE(PG8_SA(1, 1), a1 + hstep, voffA);
;             PG8_WAIT_V(8); PG8_WAIT_L(0); PG8_BAR; PG8_MMA(0, 0, At, B0); PG8_MMA(0, 1, At, B1); PG8_BAR; PG8_SCHED;
;             PG8_LDA(At, 0, 1); PG8_STAGE(PG8_SB(0, 0), b2, voffB); PG8_STAGE(PG8_SB(0, 1), b2 + hstep, voffB); PG8_STAGE(PG8_SA(0, 0), a2, voffA);
;             PG8_WAIT_V(8); PG8_WAIT_L(0); PG8_BAR; PG8_MMA(1, 0, At, B0); PG8_MMA(1, 1, At, B1); PG8_BAR; PG8_SCHED;
.LBB0_383:
	v_add_u32_e32 v1, s68, v170
	ds_read_b128 v[156:159], v1
	ds_read_b128 v[162:165], v1 offset:1024
	ds_read_b128 v[166:169], v1 offset:2048
	ds_read_b128 v[174:177], v1 offset:3072
	v_add_u32_e32 v1, s69, v170
	s_add_u32 s48, s44, s46
	ds_read_b128 v[178:181], v1
	ds_read_b128 v[182:185], v1 offset:1024
	ds_read_b128 v[186:189], v1 offset:2048
	ds_read_b128 v[190:193], v1 offset:3072
	s_addc_u32 s49, s45, s47
	s_add_u32 s48, s48, 0x100
	s_addc_u32 s49, s49, 0
	s_add_u32 s81, s78, s46
	s_addc_u32 s82, s79, s47
	s_cmpk_eq_i32 s46, 0x700
	s_cselect_b32 s51, s37, s49
	s_cselect_b32 s50, s74, s48
	s_cselect_b32 s49, s35, s82
	s_cselect_b32 s48, s75, s81
	v_lshl_add_u64 v[2:3], v[152:153], 0, s[46:47]
	s_add_i32 m0, s54, 0xc000
	ds_read_b128 v[194:197], v172
	ds_read_b128 v[198:201], v172 offset:1024
	ds_read_b128 v[202:205], v172 offset:2048
	ds_read_b128 v[206:209], v172 offset:3072
	ds_read_b128 v[210:213], v172 offset:4096
	ds_read_b128 v[214:217], v172 offset:5120
	ds_read_b128 v[218:221], v172 offset:6144
	ds_read_b128 v[222:225], v172 offset:7168
	global_load_lds_dwordx4 v[2:3], off
	v_lshl_add_u64 v[2:3], v[154:155], 0, s[46:47]
	s_add_i32 m0, s54, 0xe000
	s_nop 0
	global_load_lds_dwordx4 v[2:3], off
	s_waitcnt vmcnt(8)
	s_waitcnt lgkmcnt(0)
	s_barrier
	s_setprio 1
	s_waitcnt lgkmcnt(0)
	v_mfma_f32_16x16x32_bf16 v[128:131], v[156:159], v[194:197], v[128:131]
	v_mfma_f32_16x16x32_bf16 v[124:127], v[166:169], v[194:197], v[124:127]
	v_mfma_f32_16x16x32_bf16 v[112:115], v[156:159], v[202:205], v[112:115]
	v_mfma_f32_16x16x32_bf16 v[108:111], v[166:169], v[202:205], v[108:111]
	v_mfma_f32_16x16x32_bf16 v[96:99], v[156:159], v[210:213], v[96:99]
	v_mfma_f32_16x16x32_bf16 v[92:95], v[166:169], v[210:213], v[92:95]
	v_mfma_f32_16x16x32_bf16 v[80:83], v[156:159], v[218:221], v[80:83]
	v_mfma_f32_16x16x32_bf16 v[76:79], v[166:169], v[218:221], v[76:79]
	v_mfma_f32_16x16x32_bf16 v[128:131], v[162:165], v[198:201], v[128:131]
	v_mfma_f32_16x16x32_bf16 v[124:127], v[174:177], v[198:201], v[124:127]
	v_mfma_f32_16x16x32_bf16 v[112:115], v[162:165], v[206:209], v[112:115]
	v_mfma_f32_16x16x32_bf16 v[108:111], v[174:177], v[206:209], v[108:111]
	v_mfma_f32_16x16x32_bf16 v[96:99], v[162:165], v[214:217], v[96:99]
	v_mfma_f32_16x16x32_bf16 v[92:95], v[174:177], v[214:217], v[92:95]
	v_mfma_f32_16x16x32_bf16 v[80:83], v[162:165], v[222:225], v[80:83]
	v_mfma_f32_16x16x32_bf16 v[76:79], v[174:177], v[222:225], v[76:79]
	s_setprio 0
	s_setprio 1
	v_mfma_f32_16x16x32_bf16 v[120:123], v[178:181], v[194:197], v[120:123]
	v_mfma_f32_16x16x32_bf16 v[116:119], v[186:189], v[194:197], v[116:119]
	v_mfma_f32_16x16x32_bf16 v[104:107], v[178:181], v[202:205], v[104:107]
	v_mfma_f32_16x16x32_bf16 v[100:103], v[186:189], v[202:205], v[100:103]
	v_mfma_f32_16x16x32_bf16 v[88:91], v[178:181], v[210:213], v[88:91]
	v_mfma_f32_16x16x32_bf16 v[84:87], v[186:189], v[210:213], v[84:87]
	v_mfma_f32_16x16x32_bf16 v[72:75], v[178:181], v[218:221], v[72:75]
	v_mfma_f32_16x16x32_bf16 v[68:71], v[186:189], v[218:221], v[68:71]
	v_mfma_f32_16x16x32_bf16 v[120:123], v[182:185], v[198:201], v[120:123]
	v_mfma_f32_16x16x32_bf16 v[116:119], v[190:193], v[198:201], v[116:119]
	v_mfma_f32_16x16x32_bf16 v[104:107], v[182:185], v[206:209], v[104:107]
	v_mfma_f32_16x16x32_bf16 v[100:103], v[190:193], v[206:209], v[100:103]
	v_mfma_f32_16x16x32_bf16 v[88:91], v[182:185], v[214:217], v[88:91]
	v_mfma_f32_16x16x32_bf16 v[84:87], v[190:193], v[214:217], v[84:87]
	v_mfma_f32_16x16x32_bf16 v[72:75], v[182:185], v[222:225], v[72:75]
	v_mfma_f32_16x16x32_bf16 v[68:71], v[190:193], v[222:225], v[68:71]
	s_setprio 0
	s_barrier
	s_add_i32 s81, s68, s53
	v_lshl_add_u64 v[226:227], s[48:49], 0, v[134:135]
	s_mov_b32 m0, s81
	ds_read_b128 v[194:197], v172 offset:16384
	ds_read_b128 v[198:201], v172 offset:17408
	ds_read_b128 v[202:205], v172 offset:18432
	ds_read_b128 v[206:209], v172 offset:19456
	ds_read_b128 v[210:213], v172 offset:20480
	ds_read_b128 v[214:217], v172 offset:21504
	ds_read_b128 v[218:221], v172 offset:22528
	ds_read_b128 v[222:225], v172 offset:23552
	global_load_lds_dwordx4 v[226:227], off
	s_add_i32 m0, s81, 0x2000
	s_add_u32 s82, s48, 0x40000
	v_lshl_add_u64 v[228:229], s[48:49], 0, v[138:139]
	s_addc_u32 s83, s49, 0
	s_add_i32 s81, s69, s53
	global_load_lds_dwordx4 v[228:229], off
	v_lshl_add_u64 v[2:3], s[82:83], 0, v[134:135]
	s_mov_b32 m0, s81
	s_nop 0
	global_load_lds_dwordx4 v[2:3], off
	v_lshl_add_u64 v[2:3], s[82:83], 0, v[138:139]
	s_add_i32 m0, s81, 0x2000
	s_nop 0
	global_load_lds_dwordx4 v[2:3], off
	s_waitcnt vmcnt(6)
	s_waitcnt lgkmcnt(0)
	s_barrier
; #define PG8_STAGE(bufoff, gbase, voff) do { _Pragma("unroll") for (int _i = 0; _i < 2; ++_i) \
;         __builtin_amdgcn_global_load_lds((const unsigned*)((const char*)(gbase) + (voff)[_i]), (PG8_LAS unsigned*)(lds + (bufoff) + ldsw + _i * 8192), 16, 0, 0); } while (0)
; #define PG8_LDA(dst, b, h) do { _Pragma("unroll") for (int m = 0; m < 4; ++m) _Pragma("unroll") for (int k = 0; k < 2; ++k) dst[m][k] = *(const PG8_LAS bf16x8*)(lds + PG8_SA(b, h) + aoff + m * 2048 + k * 1024); } while (0)
; #define PG8_LDB(dst, b, h) do { _Pragma("unroll") for (int n = 0; n < 2; ++n) _Pragma("unroll") for (int k = 0; k < 2; ++k) dst[n][k] = *(const PG8_LAS bf16x8*)(lds + PG8_SB(b, h) + boff + n * 2048 + k * 1024); } while (0)
; #define PG8_MMA(ai, bj, At, Bt) do { __builtin_amdgcn_s_setprio(1); _Pragma("unroll") for (int m = 0; m < 4; ++m) _Pragma("unroll") for (int n = 0; n < 2; ++n) _Pragma("unroll") for (int k = 0; k < 2; ++k) \
;         acc[ai][bj][m][n] = __builtin_amdgcn_mfma_f32_16x16x32_bf16(Bt[n][k], At[m][k], acc[ai][bj][m][n], 0, 0, 0); __builtin_amdgcn_s_setprio(0); } while (0)
; #define PG8_WAIT_V(n) asm volatile("s_waitcnt vmcnt(" #n ")" ::: "memory")
; #define PG8_WAIT_L(n) asm volatile("s_waitcnt lgkmcnt(" #n ")" ::: "memory")
; #define PG8_BAR __builtin_amdgcn_s_barrier()
; #define PG8_SCHED __builtin_amdgcn_sched_barrier(0)
; template <class Epi, class Sched, bool ALIGN_EPI = false, bool SP2 = false>
; __device__ __forceinline__ void gemm_phase(PG8_LAS unsigned char* lds, const Gemm g, const Sched& S, const Epi& E) {
;     ...
;             PG8_WAIT_V(8); PG8_WAIT_L(0); PG8_BAR; PG8_MMA(0, 0, At, B0); PG8_MMA(0, 1, At, B1); PG8_BAR; PG8_SCHED;
;             PG8_LDA(At, 0, 1); PG8_STAGE(PG8_SB(0, 0), b2, voffB); PG8_STAGE(PG8_SB(0, 1), b2 + hstep, voffB); PG8_STAGE(PG8_SA(0, 0), a2, voffA);
;             PG8_WAIT_V(8); PG8_WAIT_L(0); PG8_BAR; PG8_MMA(1, 0, At, B0); PG8_MMA(1, 1, At, B1); PG8_BAR; PG8_SCHED;
;             PG8_LDB(B0, 1, 0); PG8_LDB(B1, 1, 1); PG8_SCHED; PG8_LDA(At, 1, 0); PG8_STAGE(PG8_SA(0, 1), a2 + hstep, voffA);
;             PG8_WAIT_V(8); PG8_WAIT_L(0); PG8_BAR; PG8_MMA(0, 0, At, B0); PG8_MMA(0, 1, At, B1); PG8_BAR; PG8_SCHED;
	s_setprio 1
	s_waitcnt lgkmcnt(0)
	v_mfma_f32_16x16x32_bf16 v[64:67], v[156:159], v[194:197], v[64:67]
	v_mfma_f32_16x16x32_bf16 v[60:63], v[166:169], v[194:197], v[60:63]
	v_mfma_f32_16x16x32_bf16 v[48:51], v[156:159], v[202:205], v[48:51]
	v_mfma_f32_16x16x32_bf16 v[44:47], v[166:169], v[202:205], v[44:47]
	v_mfma_f32_16x16x32_bf16 v[32:35], v[156:159], v[210:213], v[32:35]
	v_mfma_f32_16x16x32_bf16 v[28:31], v[166:169], v[210:213], v[28:31]
	v_mfma_f32_16x16x32_bf16 v[16:19], v[156:159], v[218:221], v[16:19]
	v_mfma_f32_16x16x32_bf16 v[12:15], v[166:169], v[218:221], v[12:15]
	v_mfma_f32_16x16x32_bf16 v[64:67], v[162:165], v[198:201], v[64:67]
	v_mfma_f32_16x16x32_bf16 v[60:63], v[174:177], v[198:201], v[60:63]
	v_mfma_f32_16x16x32_bf16 v[48:51], v[162:165], v[206:209], v[48:51]
	v_mfma_f32_16x16x32_bf16 v[44:47], v[174:177], v[206:209], v[44:47]
	v_mfma_f32_16x16x32_bf16 v[32:35], v[162:165], v[214:217], v[32:35]
	v_mfma_f32_16x16x32_bf16 v[28:31], v[174:177], v[214:217], v[28:31]
	v_mfma_f32_16x16x32_bf16 v[16:19], v[162:165], v[222:225], v[16:19]
	v_mfma_f32_16x16x32_bf16 v[12:15], v[174:177], v[222:225], v[12:15]
	s_setprio 0
	s_setprio 1
	v_mfma_f32_16x16x32_bf16 v[56:59], v[178:181], v[194:197], v[56:59]
	v_mfma_f32_16x16x32_bf16 v[52:55], v[186:189], v[194:197], v[52:55]
	v_mfma_f32_16x16x32_bf16 v[40:43], v[178:181], v[202:205], v[40:43]
	v_mfma_f32_16x16x32_bf16 v[36:39], v[186:189], v[202:205], v[36:39]
	v_mfma_f32_16x16x32_bf16 v[24:27], v[178:181], v[210:213], v[24:27]
	v_mfma_f32_16x16x32_bf16 v[20:23], v[186:189], v[210:213], v[20:23]
	v_mfma_f32_16x16x32_bf16 v[8:11], v[178:181], v[218:221], v[8:11]
	v_mfma_f32_16x16x32_bf16 v[2:5], v[186:189], v[218:221], v[4:7]
	v_mfma_f32_16x16x32_bf16 v[56:59], v[182:185], v[198:201], v[56:59]
	v_mfma_f32_16x16x32_bf16 v[52:55], v[190:193], v[198:201], v[52:55]
	v_mfma_f32_16x16x32_bf16 v[40:43], v[182:185], v[206:209], v[40:43]
	v_mfma_f32_16x16x32_bf16 v[36:39], v[190:193], v[206:209], v[36:39]
	v_mfma_f32_16x16x32_bf16 v[24:27], v[182:185], v[214:217], v[24:27]
	v_mfma_f32_16x16x32_bf16 v[20:23], v[190:193], v[214:217], v[20:23]
	v_mfma_f32_16x16x32_bf16 v[8:11], v[182:185], v[222:225], v[8:11]
	v_mfma_f32_16x16x32_bf16 v[2:5], v[190:193], v[222:225], v[2:5]
	s_setprio 0
	s_barrier
	s_add_i32 s81, 0, 0x18000
	v_add_u32_e32 v1, s81, v170
	s_add_i32 s82, 0, 0x1c000
	ds_read_b128 v[156:159], v1
	ds_read_b128 v[162:165], v1 offset:1024
	ds_read_b128 v[166:169], v1 offset:2048
	ds_read_b128 v[174:177], v1 offset:3072
	v_add_u32_e32 v1, s82, v170
	ds_read_b128 v[178:181], v1
	ds_read_b128 v[182:185], v1 offset:1024
	ds_read_b128 v[186:189], v1 offset:2048
	ds_read_b128 v[190:193], v1 offset:3072
	v_lshl_add_u64 v[230:231], s[50:51], 0, v[132:133]
	v_lshl_add_u64 v[232:233], s[50:51], 0, v[136:137]
	s_mov_b32 m0, s54
	s_nop 0
	global_load_lds_dwordx4 v[230:231], off
	s_mov_b32 m0, s55
	s_nop 0
	global_load_lds_dwordx4 v[232:233], off
	s_add_u32 s50, s50, 0x40000
	s_addc_u32 s51, s51, 0
	s_mov_b32 m0, s62
	v_lshl_add_u64 v[6:7], s[50:51], 0, v[132:133]
	ds_read_b128 v[194:197], v172 offset:32768
	ds_read_b128 v[198:201], v172 offset:33792
	ds_read_b128 v[202:205], v172 offset:34816
	ds_read_b128 v[206:209], v172 offset:35840
	ds_read_b128 v[210:213], v172 offset:36864
	ds_read_b128 v[214:217], v172 offset:37888
	ds_read_b128 v[218:221], v172 offset:38912
	ds_read_b128 v[222:225], v172 offset:39936
	global_load_lds_dwordx4 v[6:7], off
	v_lshl_add_u64 v[6:7], s[50:51], 0, v[136:137]
	s_mov_b32 m0, s63
	s_nop 0
	global_load_lds_dwordx4 v[6:7], off
	s_waitcnt vmcnt(8)
	s_waitcnt lgkmcnt(0)
	s_barrier
; #define PG8_STAGE(bufoff, gbase, voff) do { _Pragma("unroll") for (int _i = 0; _i < 2; ++_i) \
;         __builtin_amdgcn_global_load_lds((const unsigned*)((const char*)(gbase) + (voff)[_i]), (PG8_LAS unsigned*)(lds + (bufoff) + ldsw + _i * 8192), 16, 0, 0); } while (0)
; #define PG8_LDA(dst, b, h) do { _Pragma("unroll") for (int m = 0; m < 4; ++m) _Pragma("unroll") for (int k = 0; k < 2; ++k) dst[m][k] = *(const PG8_LAS bf16x8*)(lds + PG8_SA(b, h) + aoff + m * 2048 + k * 1024); } while (0)
; #define PG8_MMA(ai, bj, At, Bt) do { __builtin_amdgcn_s_setprio(1); _Pragma("unroll") for (int m = 0; m < 4; ++m) _Pragma("unroll") for (int n = 0; n < 2; ++n) _Pragma("unroll") for (int k = 0; k < 2; ++k) \
;         acc[ai][bj][m][n] = __builtin_amdgcn_mfma_f32_16x16x32_bf16(Bt[n][k], At[m][k], acc[ai][bj][m][n], 0, 0, 0); __builtin_amdgcn_s_setprio(0); } while (0)
; #define PG8_WAIT_V(n) asm volatile("s_waitcnt vmcnt(" #n ")" ::: "memory")
; #define PG8_WAIT_L(n) asm volatile("s_waitcnt lgkmcnt(" #n ")" ::: "memory")
; #define PG8_BAR __builtin_amdgcn_s_barrier()
; #define PG8_SCHED __builtin_amdgcn_sched_barrier(0)
; template <class Epi, class Sched, bool ALIGN_EPI = false, bool SP2 = false>
; __device__ __forceinline__ void gemm_phase(PG8_LAS unsigned char* lds, const Gemm g, const Sched& S, const Epi& E) {
;     ...
;             PG8_WAIT_V(8); PG8_WAIT_L(0); PG8_BAR; PG8_MMA(0, 0, At, B0); PG8_MMA(0, 1, At, B1); PG8_BAR; PG8_SCHED;
;             PG8_LDA(At, 1, 1); PG8_STAGE(PG8_SB(1, 0), b3, voffB); PG8_STAGE(PG8_SB(1, 1), b3 + hstep, voffB); PG8_STAGE(PG8_SA(1, 0), a3, voffA);
;             PG8_WAIT_V(8); PG8_WAIT_L(0); PG8_BAR; PG8_MMA(1, 0, At, B0); PG8_MMA(1, 1, At, B1); PG8_BAR; PG8_SCHED;
	s_setprio 1
	s_waitcnt lgkmcnt(0)
	v_mfma_f32_16x16x32_bf16 v[128:131], v[156:159], v[194:197], v[128:131]
	v_mfma_f32_16x16x32_bf16 v[124:127], v[166:169], v[194:197], v[124:127]
	v_mfma_f32_16x16x32_bf16 v[112:115], v[156:159], v[202:205], v[112:115]
	v_mfma_f32_16x16x32_bf16 v[108:111], v[166:169], v[202:205], v[108:111]
	v_mfma_f32_16x16x32_bf16 v[96:99], v[156:159], v[210:213], v[96:99]
	v_mfma_f32_16x16x32_bf16 v[92:95], v[166:169], v[210:213], v[92:95]
	v_mfma_f32_16x16x32_bf16 v[80:83], v[156:159], v[218:221], v[80:83]
	v_mfma_f32_16x16x32_bf16 v[76:79], v[166:169], v[218:221], v[76:79]
	v_mfma_f32_16x16x32_bf16 v[128:131], v[162:165], v[198:201], v[128:131]
	v_mfma_f32_16x16x32_bf16 v[124:127], v[174:177], v[198:201], v[124:127]
	v_mfma_f32_16x16x32_bf16 v[112:115], v[162:165], v[206:209], v[112:115]
	v_mfma_f32_16x16x32_bf16 v[108:111], v[174:177], v[206:209], v[108:111]
	v_mfma_f32_16x16x32_bf16 v[96:99], v[162:165], v[214:217], v[96:99]
	v_mfma_f32_16x16x32_bf16 v[92:95], v[174:177], v[214:217], v[92:95]
	v_mfma_f32_16x16x32_bf16 v[80:83], v[162:165], v[222:225], v[80:83]
	v_mfma_f32_16x16x32_bf16 v[76:79], v[174:177], v[222:225], v[76:79]
	s_setprio 0
	s_setprio 1
	v_mfma_f32_16x16x32_bf16 v[120:123], v[178:181], v[194:197], v[120:123]
	v_mfma_f32_16x16x32_bf16 v[116:119], v[186:189], v[194:197], v[116:119]
	v_mfma_f32_16x16x32_bf16 v[104:107], v[178:181], v[202:205], v[104:107]
	v_mfma_f32_16x16x32_bf16 v[100:103], v[186:189], v[202:205], v[100:103]
	v_mfma_f32_16x16x32_bf16 v[88:91], v[178:181], v[210:213], v[88:91]
	v_mfma_f32_16x16x32_bf16 v[84:87], v[186:189], v[210:213], v[84:87]
	v_mfma_f32_16x16x32_bf16 v[72:75], v[178:181], v[218:221], v[72:75]
	v_mfma_f32_16x16x32_bf16 v[68:71], v[186:189], v[218:221], v[68:71]
	v_mfma_f32_16x16x32_bf16 v[120:123], v[182:185], v[198:201], v[120:123]
	v_mfma_f32_16x16x32_bf16 v[116:119], v[190:193], v[198:201], v[116:119]
	v_mfma_f32_16x16x32_bf16 v[104:107], v[182:185], v[206:209], v[104:107]
	v_mfma_f32_16x16x32_bf16 v[100:103], v[190:193], v[206:209], v[100:103]
	v_mfma_f32_16x16x32_bf16 v[88:91], v[182:185], v[214:217], v[88:91]
	v_mfma_f32_16x16x32_bf16 v[84:87], v[190:193], v[214:217], v[84:87]
	v_mfma_f32_16x16x32_bf16 v[72:75], v[182:185], v[222:225], v[72:75]
	v_mfma_f32_16x16x32_bf16 v[68:71], v[190:193], v[222:225], v[68:71]
	s_setprio 0
	s_barrier
	s_add_i32 s50, s81, s53
	v_lshl_add_u64 v[6:7], v[226:227], 0, s[12:13]
	s_mov_b32 m0, s50
	ds_read_b128 v[194:197], v172 offset:49152
	ds_read_b128 v[198:201], v172 offset:50176
	ds_read_b128 v[202:205], v172 offset:51200
	ds_read_b128 v[206:209], v172 offset:52224
	ds_read_b128 v[210:213], v172 offset:53248
	ds_read_b128 v[214:217], v172 offset:54272
	ds_read_b128 v[218:221], v172 offset:55296
	ds_read_b128 v[222:225], v172 offset:56320
	global_load_lds_dwordx4 v[6:7], off
	s_add_i32 m0, s50, 0x2000
	s_add_u32 s48, s48, 0x40080
	v_lshl_add_u64 v[6:7], v[228:229], 0, s[12:13]
	s_addc_u32 s49, s49, 0
	s_add_i32 s50, s82, s53
	global_load_lds_dwordx4 v[6:7], off
	v_lshl_add_u64 v[6:7], s[48:49], 0, v[134:135]
	s_mov_b32 m0, s50
	s_nop 0
	global_load_lds_dwordx4 v[6:7], off
	v_lshl_add_u64 v[6:7], s[48:49], 0, v[138:139]
	s_add_i32 m0, s50, 0x2000
	s_nop 0
	global_load_lds_dwordx4 v[6:7], off
	v_lshl_add_u64 v[6:7], v[230:231], 0, s[12:13]
	s_mov_b32 m0, s65
	s_nop 0
	global_load_lds_dwordx4 v[6:7], off
	v_lshl_add_u64 v[6:7], v[232:233], 0, s[12:13]
	s_mov_b32 m0, s66
	s_nop 0
	global_load_lds_dwordx4 v[6:7], off
	s_waitcnt vmcnt(8)
	s_waitcnt lgkmcnt(0)
	s_barrier
	s_setprio 1
	s_waitcnt lgkmcnt(0)
	v_mfma_f32_16x16x32_bf16 v[64:67], v[156:159], v[194:197], v[64:67]
	v_mfma_f32_16x16x32_bf16 v[60:63], v[166:169], v[194:197], v[60:63]
	v_mfma_f32_16x16x32_bf16 v[48:51], v[156:159], v[202:205], v[48:51]
	v_mfma_f32_16x16x32_bf16 v[44:47], v[166:169], v[202:205], v[44:47]
	v_mfma_f32_16x16x32_bf16 v[32:35], v[156:159], v[210:213], v[32:35]
	v_mfma_f32_16x16x32_bf16 v[28:31], v[166:169], v[210:213], v[28:31]
	v_mfma_f32_16x16x32_bf16 v[16:19], v[156:159], v[218:221], v[16:19]
	v_mfma_f32_16x16x32_bf16 v[12:15], v[166:169], v[218:221], v[12:15]
	v_mfma_f32_16x16x32_bf16 v[64:67], v[162:165], v[198:201], v[64:67]
	v_mfma_f32_16x16x32_bf16 v[60:63], v[174:177], v[198:201], v[60:63]
	v_mfma_f32_16x16x32_bf16 v[48:51], v[162:165], v[206:209], v[48:51]
	v_mfma_f32_16x16x32_bf16 v[44:47], v[174:177], v[206:209], v[44:47]
	v_mfma_f32_16x16x32_bf16 v[32:35], v[162:165], v[214:217], v[32:35]
	v_mfma_f32_16x16x32_bf16 v[28:31], v[174:177], v[214:217], v[28:31]
	v_mfma_f32_16x16x32_bf16 v[16:19], v[162:165], v[222:225], v[16:19]
	v_mfma_f32_16x16x32_bf16 v[12:15], v[174:177], v[222:225], v[12:15]
	s_setprio 0
	s_setprio 1
	v_mfma_f32_16x16x32_bf16 v[56:59], v[178:181], v[194:197], v[56:59]
	v_mfma_f32_16x16x32_bf16 v[52:55], v[186:189], v[194:197], v[52:55]
	v_mfma_f32_16x16x32_bf16 v[40:43], v[178:181], v[202:205], v[40:43]
	v_mfma_f32_16x16x32_bf16 v[36:39], v[186:189], v[202:205], v[36:39]
	v_mfma_f32_16x16x32_bf16 v[24:27], v[178:181], v[210:213], v[24:27]
	v_mfma_f32_16x16x32_bf16 v[20:23], v[186:189], v[210:213], v[20:23]
	v_mfma_f32_16x16x32_bf16 v[6:9], v[178:181], v[218:221], v[8:11]
	v_mfma_f32_16x16x32_bf16 v[2:5], v[186:189], v[218:221], v[2:5]
	v_mfma_f32_16x16x32_bf16 v[56:59], v[182:185], v[198:201], v[56:59]
	v_mfma_f32_16x16x32_bf16 v[52:55], v[190:193], v[198:201], v[52:55]
	v_mfma_f32_16x16x32_bf16 v[40:43], v[182:185], v[206:209], v[40:43]
	v_mfma_f32_16x16x32_bf16 v[36:39], v[190:193], v[206:209], v[36:39]
	v_mfma_f32_16x16x32_bf16 v[24:27], v[182:185], v[214:217], v[24:27]
	v_mfma_f32_16x16x32_bf16 v[20:23], v[190:193], v[214:217], v[20:23]
	v_mfma_f32_16x16x32_bf16 v[8:11], v[182:185], v[222:225], v[6:9]
	v_mfma_f32_16x16x32_bf16 v[4:7], v[190:193], v[222:225], v[2:5]
	s_setprio 0
	s_barrier
	s_add_i32 s80, s80, 2
	s_add_u32 s46, s46, 0x100
	s_addc_u32 s47, s47, 0
	s_cmp_gt_u32 s80, 13
	s_cbranch_scc1 .LBB0_386

; #define PG8_STAGE(bufoff, gbase, voff) do { _Pragma("unroll") for (int _i = 0; _i < 2; ++_i) \
;         __builtin_amdgcn_global_load_lds((const unsigned*)((const char*)(gbase) + (voff)[_i]), (PG8_LAS unsigned*)(lds + (bufoff) + ldsw + _i * 8192), 16, 0, 0); } while (0)
; #define PG8_LDA(dst, b, h) do { _Pragma("unroll") for (int m = 0; m < 4; ++m) _Pragma("unroll") for (int k = 0; k < 2; ++k) dst[m][k] = *(const PG8_LAS bf16x8*)(lds + PG8_SA(b, h) + aoff + m * 2048 + k * 1024); } while (0)
; #define PG8_LDB(dst, b, h) do { _Pragma("unroll") for (int n = 0; n < 2; ++n) _Pragma("unroll") for (int k = 0; k < 2; ++k) dst[n][k] = *(const PG8_LAS bf16x8*)(lds + PG8_SB(b, h) + boff + n * 2048 + k * 1024); } while (0)
; #define PG8_MMA(ai, bj, At, Bt) do { __builtin_amdgcn_s_setprio(1); _Pragma("unroll") for (int m = 0; m < 4; ++m) _Pragma("unroll") for (int n = 0; n < 2; ++n) _Pragma("unroll") for (int k = 0; k < 2; ++k) \
;         acc[ai][bj][m][n] = __builtin_amdgcn_mfma_f32_16x16x32_bf16(Bt[n][k], At[m][k], acc[ai][bj][m][n], 0, 0, 0); __builtin_amdgcn_s_setprio(0); } while (0)
; #define PG8_WAIT_V(n) asm volatile("s_waitcnt vmcnt(" #n ")" ::: "memory")
; #define PG8_WAIT_L(n) asm volatile("s_waitcnt lgkmcnt(" #n ")" ::: "memory")
; template <class Epi, class Sched, bool ALIGN_EPI = false, bool SP2 = false>
; __device__ __forceinline__ void gemm_phase(PG8_LAS unsigned char* lds, const Gemm g, const Sched& S, const Epi& E) {
;     ...
;             const bool last = (t == nt - 2);
;             const char* a1 = cA + (size_t)(t + 1) * kstep;
;             const char* a2 = last ? nA : cA + (size_t)(t + 2) * kstep; const char* b2 = last ? nB : cB + (size_t)(t + 2) * kstep;
;             const char* a3 = a2 + kstep; const char* b3 = b2 + kstep;
;             if (last && has_next) S.a_ready(nxt);
;             if constexpr (SP2) {
;             PG8_LDB(B0, 0, 0); PG8_LDB(B1, 0, 1); PG8_SCHED; PG8_LDA(At, 0, 0); PG8_STAGE(PG8_SA(1, 1), a1 + hstep, voffA);
;             PG8_WAIT_V(8); PG8_WAIT_L(0); PG8_BAR; PG8_MMA(0, 0, At, B0); PG8_MMA(0, 1, At, B1); PG8_BAR; PG8_SCHED;
;             PG8_LDA(At, 0, 1); PG8_STAGE(PG8_SB(0, 0), b2, voffB); PG8_STAGE(PG8_SB(0, 1), b2 + hstep, voffB); PG8_STAGE(PG8_SA(0, 0), a2, voffA);
;             PG8_WAIT_V(8); PG8_WAIT_L(0); PG8_BAR; PG8_MMA(1, 0, At, B0); PG8_MMA(1, 1, At, B1); PG8_BAR; PG8_SCHED;
.LBB0_466:
	ds_read_b128 v[144:147], v151
	ds_read_b128 v[156:159], v151 offset:1024
	ds_read_b128 v[162:165], v151 offset:2048
	ds_read_b128 v[166:169], v151 offset:3072
	ds_read_b128 v[170:173], v152
	ds_read_b128 v[174:177], v152 offset:1024
	ds_read_b128 v[178:181], v152 offset:2048
	ds_read_b128 v[182:185], v152 offset:3072
	s_add_u32 s34, s30, 0xfffc0080
	s_addc_u32 s35, s31, -1
	s_cmp_eq_u32 s55, 12
	s_cselect_b32 s37, s23, s35
	s_cselect_b32 s36, s29, s34
	s_cselect_b32 s35, s21, s54
	s_cselect_b32 s34, s52, s53
	v_lshl_add_u64 v[218:219], s[30:31], 0, v[136:137]
	s_add_i32 m0, s39, 0xc000
	ds_read_b128 v[186:189], v153
	ds_read_b128 v[190:193], v153 offset:1024
	ds_read_b128 v[194:197], v153 offset:2048
	ds_read_b128 v[198:201], v153 offset:3072
	ds_read_b128 v[202:205], v153 offset:4096
	ds_read_b128 v[206:209], v153 offset:5120
	ds_read_b128 v[210:213], v153 offset:6144
	ds_read_b128 v[214:217], v153 offset:7168
	global_load_lds_dwordx4 v[218:219], off
	v_lshl_add_u64 v[218:219], s[30:31], 0, v[138:139]
	s_add_i32 m0, s39, 0xe000
	s_nop 0
	global_load_lds_dwordx4 v[218:219], off
	s_waitcnt vmcnt(8)
	s_waitcnt lgkmcnt(0)
	s_barrier
	s_setprio 1
	s_waitcnt lgkmcnt(0)
	v_mfma_f32_16x16x32_bf16 v[124:127], v[144:147], v[186:189], v[124:127]
	v_mfma_f32_16x16x32_bf16 v[120:123], v[162:165], v[186:189], v[120:123]
	v_mfma_f32_16x16x32_bf16 v[108:111], v[144:147], v[194:197], v[108:111]
	v_mfma_f32_16x16x32_bf16 v[104:107], v[162:165], v[194:197], v[104:107]
	v_mfma_f32_16x16x32_bf16 v[92:95], v[144:147], v[202:205], v[92:95]
	v_mfma_f32_16x16x32_bf16 v[88:91], v[162:165], v[202:205], v[88:91]
	v_mfma_f32_16x16x32_bf16 v[76:79], v[144:147], v[210:213], v[76:79]
	v_mfma_f32_16x16x32_bf16 v[72:75], v[162:165], v[210:213], v[72:75]
	v_mfma_f32_16x16x32_bf16 v[124:127], v[156:159], v[190:193], v[124:127]
	v_mfma_f32_16x16x32_bf16 v[120:123], v[166:169], v[190:193], v[120:123]
	v_mfma_f32_16x16x32_bf16 v[108:111], v[156:159], v[198:201], v[108:111]
	v_mfma_f32_16x16x32_bf16 v[104:107], v[166:169], v[198:201], v[104:107]
	v_mfma_f32_16x16x32_bf16 v[92:95], v[156:159], v[206:209], v[92:95]
	v_mfma_f32_16x16x32_bf16 v[88:91], v[166:169], v[206:209], v[88:91]
	v_mfma_f32_16x16x32_bf16 v[76:79], v[156:159], v[214:217], v[76:79]
	v_mfma_f32_16x16x32_bf16 v[72:75], v[166:169], v[214:217], v[72:75]
	s_setprio 0
	s_setprio 1
	v_mfma_f32_16x16x32_bf16 v[116:119], v[170:173], v[186:189], v[116:119]
	v_mfma_f32_16x16x32_bf16 v[112:115], v[178:181], v[186:189], v[112:115]
	v_mfma_f32_16x16x32_bf16 v[100:103], v[170:173], v[194:197], v[100:103]
	v_mfma_f32_16x16x32_bf16 v[96:99], v[178:181], v[194:197], v[96:99]
	v_mfma_f32_16x16x32_bf16 v[84:87], v[170:173], v[202:205], v[84:87]
	v_mfma_f32_16x16x32_bf16 v[80:83], v[178:181], v[202:205], v[80:83]
	v_mfma_f32_16x16x32_bf16 v[68:71], v[170:173], v[210:213], v[68:71]
	v_mfma_f32_16x16x32_bf16 v[64:67], v[178:181], v[210:213], v[64:67]
	v_mfma_f32_16x16x32_bf16 v[116:119], v[174:177], v[190:193], v[116:119]
	v_mfma_f32_16x16x32_bf16 v[112:115], v[182:185], v[190:193], v[112:115]
	v_mfma_f32_16x16x32_bf16 v[100:103], v[174:177], v[198:201], v[100:103]
	v_mfma_f32_16x16x32_bf16 v[96:99], v[182:185], v[198:201], v[96:99]
	v_mfma_f32_16x16x32_bf16 v[84:87], v[174:177], v[206:209], v[84:87]
	v_mfma_f32_16x16x32_bf16 v[80:83], v[182:185], v[206:209], v[80:83]
	v_mfma_f32_16x16x32_bf16 v[68:71], v[174:177], v[214:217], v[68:71]
	v_mfma_f32_16x16x32_bf16 v[64:67], v[182:185], v[214:217], v[64:67]
	s_setprio 0
	s_barrier
	s_add_i32 s62, s49, s38
	v_lshl_add_u64 v[218:219], s[34:35], 0, v[130:131]
	s_mov_b32 m0, s62
	ds_read_b128 v[186:189], v153 offset:16384
	ds_read_b128 v[190:193], v153 offset:17408
	ds_read_b128 v[194:197], v153 offset:18432
	ds_read_b128 v[198:201], v153 offset:19456
	ds_read_b128 v[202:205], v153 offset:20480
	ds_read_b128 v[206:209], v153 offset:21504
	ds_read_b128 v[210:213], v153 offset:22528
	ds_read_b128 v[214:217], v153 offset:23552
	global_load_lds_dwordx4 v[218:219], off
	s_add_i32 m0, s62, 0x2000
	s_add_u32 s62, s34, 0x40000
	v_lshl_add_u64 v[220:221], s[34:35], 0, v[134:135]
	s_addc_u32 s63, s35, 0
	s_add_i32 s64, s50, s38
	global_load_lds_dwordx4 v[220:221], off
	v_lshl_add_u64 v[222:223], s[62:63], 0, v[130:131]
	s_mov_b32 m0, s64
	s_nop 0
	global_load_lds_dwordx4 v[222:223], off
	v_lshl_add_u64 v[222:223], s[62:63], 0, v[134:135]
	s_add_i32 m0, s64, 0x2000
	s_nop 0
	global_load_lds_dwordx4 v[222:223], off
	s_nop 0
	s_waitcnt vmcnt(6)
	s_waitcnt lgkmcnt(0)
	s_barrier
; #define PG8_STAGE(bufoff, gbase, voff) do { _Pragma("unroll") for (int _i = 0; _i < 2; ++_i) \
;         __builtin_amdgcn_global_load_lds((const unsigned*)((const char*)(gbase) + (voff)[_i]), (PG8_LAS unsigned*)(lds + (bufoff) + ldsw + _i * 8192), 16, 0, 0); } while (0)
; #define PG8_LDA(dst, b, h) do { _Pragma("unroll") for (int m = 0; m < 4; ++m) _Pragma("unroll") for (int k = 0; k < 2; ++k) dst[m][k] = *(const PG8_LAS bf16x8*)(lds + PG8_SA(b, h) + aoff + m * 2048 + k * 1024); } while (0)
; #define PG8_LDB(dst, b, h) do { _Pragma("unroll") for (int n = 0; n < 2; ++n) _Pragma("unroll") for (int k = 0; k < 2; ++k) dst[n][k] = *(const PG8_LAS bf16x8*)(lds + PG8_SB(b, h) + boff + n * 2048 + k * 1024); } while (0)
; #define PG8_MMA(ai, bj, At, Bt) do { __builtin_amdgcn_s_setprio(1); _Pragma("unroll") for (int m = 0; m < 4; ++m) _Pragma("unroll") for (int n = 0; n < 2; ++n) _Pragma("unroll") for (int k = 0; k < 2; ++k) \
;         acc[ai][bj][m][n] = __builtin_amdgcn_mfma_f32_16x16x32_bf16(Bt[n][k], At[m][k], acc[ai][bj][m][n], 0, 0, 0); __builtin_amdgcn_s_setprio(0); } while (0)
; #define PG8_WAIT_V(n) asm volatile("s_waitcnt vmcnt(" #n ")" ::: "memory")
; #define PG8_WAIT_L(n) asm volatile("s_waitcnt lgkmcnt(" #n ")" ::: "memory")
; #define PG8_BAR __builtin_amdgcn_s_barrier()
; #define PG8_SCHED __builtin_amdgcn_sched_barrier(0)
; template <class Epi, class Sched, bool ALIGN_EPI = false, bool SP2 = false>
; __device__ __forceinline__ void gemm_phase(PG8_LAS unsigned char* lds, const Gemm g, const Sched& S, const Epi& E) {
;     ...
;             PG8_WAIT_V(8); PG8_WAIT_L(0); PG8_BAR; PG8_MMA(0, 0, At, B0); PG8_MMA(0, 1, At, B1); PG8_BAR; PG8_SCHED;
;             PG8_LDA(At, 0, 1); PG8_STAGE(PG8_SB(0, 0), b2, voffB); PG8_STAGE(PG8_SB(0, 1), b2 + hstep, voffB); PG8_STAGE(PG8_SA(0, 0), a2, voffA);
;             PG8_WAIT_V(8); PG8_WAIT_L(0); PG8_BAR; PG8_MMA(1, 0, At, B0); PG8_MMA(1, 1, At, B1); PG8_BAR; PG8_SCHED;
;             PG8_LDB(B0, 1, 0); PG8_LDB(B1, 1, 1); PG8_SCHED; PG8_LDA(At, 1, 0); PG8_STAGE(PG8_SA(0, 1), a2 + hstep, voffA);
;             PG8_WAIT_V(8); PG8_WAIT_L(0); PG8_BAR; PG8_MMA(0, 0, At, B0); PG8_MMA(0, 1, At, B1); PG8_BAR; PG8_SCHED;
	s_setprio 1
	s_waitcnt lgkmcnt(0)
	v_mfma_f32_16x16x32_bf16 v[60:63], v[144:147], v[186:189], v[60:63]
	v_mfma_f32_16x16x32_bf16 v[56:59], v[162:165], v[186:189], v[56:59]
	v_mfma_f32_16x16x32_bf16 v[44:47], v[144:147], v[194:197], v[44:47]
	v_mfma_f32_16x16x32_bf16 v[40:43], v[162:165], v[194:197], v[40:43]
	v_mfma_f32_16x16x32_bf16 v[28:31], v[144:147], v[202:205], v[28:31]
	v_mfma_f32_16x16x32_bf16 v[24:27], v[162:165], v[202:205], v[24:27]
	v_mfma_f32_16x16x32_bf16 v[12:15], v[144:147], v[210:213], v[12:15]
	v_mfma_f32_16x16x32_bf16 v[8:11], v[162:165], v[210:213], v[8:11]
	v_mfma_f32_16x16x32_bf16 v[60:63], v[156:159], v[190:193], v[60:63]
	v_mfma_f32_16x16x32_bf16 v[56:59], v[166:169], v[190:193], v[56:59]
	v_mfma_f32_16x16x32_bf16 v[44:47], v[156:159], v[198:201], v[44:47]
	v_mfma_f32_16x16x32_bf16 v[40:43], v[166:169], v[198:201], v[40:43]
	v_mfma_f32_16x16x32_bf16 v[28:31], v[156:159], v[206:209], v[28:31]
	v_mfma_f32_16x16x32_bf16 v[24:27], v[166:169], v[206:209], v[24:27]
	v_mfma_f32_16x16x32_bf16 v[12:15], v[156:159], v[214:217], v[12:15]
	v_mfma_f32_16x16x32_bf16 v[8:11], v[166:169], v[214:217], v[8:11]
	s_setprio 0
	s_setprio 1
	v_mfma_f32_16x16x32_bf16 v[52:55], v[170:173], v[186:189], v[52:55]
	v_mfma_f32_16x16x32_bf16 v[48:51], v[178:181], v[186:189], v[48:51]
	v_mfma_f32_16x16x32_bf16 v[36:39], v[170:173], v[194:197], v[36:39]
	v_mfma_f32_16x16x32_bf16 v[32:35], v[178:181], v[194:197], v[32:35]
	v_mfma_f32_16x16x32_bf16 v[20:23], v[170:173], v[202:205], v[20:23]
	v_mfma_f32_16x16x32_bf16 v[16:19], v[178:181], v[202:205], v[16:19]
	v_mfma_f32_16x16x32_bf16 v[4:7], v[170:173], v[210:213], v[4:7]
	v_mfma_f32_16x16x32_bf16 v[0:3], v[178:181], v[210:213], v[0:3]
	v_mfma_f32_16x16x32_bf16 v[52:55], v[174:177], v[190:193], v[52:55]
	v_mfma_f32_16x16x32_bf16 v[48:51], v[182:185], v[190:193], v[48:51]
	v_mfma_f32_16x16x32_bf16 v[36:39], v[174:177], v[198:201], v[36:39]
	v_mfma_f32_16x16x32_bf16 v[32:35], v[182:185], v[198:201], v[32:35]
	v_mfma_f32_16x16x32_bf16 v[20:23], v[174:177], v[206:209], v[20:23]
	v_mfma_f32_16x16x32_bf16 v[16:19], v[182:185], v[206:209], v[16:19]
	v_mfma_f32_16x16x32_bf16 v[4:7], v[174:177], v[214:217], v[4:7]
	v_mfma_f32_16x16x32_bf16 v[0:3], v[182:185], v[214:217], v[0:3]
	s_setprio 0
	s_barrier
	s_add_i32 s62, 0, 0x18000
	v_add_u32_e32 v155, s62, v149
	s_add_i32 s63, 0, 0x1c000
	ds_read_b128 v[144:147], v155
	ds_read_b128 v[156:159], v155 offset:1024
	ds_read_b128 v[162:165], v155 offset:2048
	ds_read_b128 v[166:169], v155 offset:3072
	v_add_u32_e32 v155, s63, v149
	ds_read_b128 v[170:173], v155
	ds_read_b128 v[174:177], v155 offset:1024
	ds_read_b128 v[178:181], v155 offset:2048
	ds_read_b128 v[182:185], v155 offset:3072
	v_lshl_add_u64 v[224:225], s[36:37], 0, v[132:133]
	v_lshl_add_u64 v[222:223], s[36:37], 0, v[128:129]
	s_mov_b32 m0, s39
	s_nop 0
	global_load_lds_dwordx4 v[222:223], off
	s_mov_b32 m0, s40
	s_nop 0
	global_load_lds_dwordx4 v[224:225], off
	s_add_u32 s36, s36, 0x40000
	s_addc_u32 s37, s37, 0
	s_mov_b32 m0, s41
	v_lshl_add_u64 v[226:227], s[36:37], 0, v[128:129]
	ds_read_b128 v[186:189], v153 offset:32768
	ds_read_b128 v[190:193], v153 offset:33792
	ds_read_b128 v[194:197], v153 offset:34816
	ds_read_b128 v[198:201], v153 offset:35840
	ds_read_b128 v[202:205], v153 offset:36864
	ds_read_b128 v[206:209], v153 offset:37888
	ds_read_b128 v[210:213], v153 offset:38912
	ds_read_b128 v[214:217], v153 offset:39936
	global_load_lds_dwordx4 v[226:227], off
	v_lshl_add_u64 v[226:227], s[36:37], 0, v[132:133]
	s_mov_b32 m0, s43
	s_nop 0
	global_load_lds_dwordx4 v[226:227], off
	s_waitcnt vmcnt(8)
	s_waitcnt lgkmcnt(0)
	s_barrier
	s_setprio 1
	s_waitcnt lgkmcnt(0)
	v_mfma_f32_16x16x32_bf16 v[124:127], v[144:147], v[186:189], v[124:127]
	v_mfma_f32_16x16x32_bf16 v[120:123], v[162:165], v[186:189], v[120:123]
	v_mfma_f32_16x16x32_bf16 v[108:111], v[144:147], v[194:197], v[108:111]
	v_mfma_f32_16x16x32_bf16 v[104:107], v[162:165], v[194:197], v[104:107]
	v_mfma_f32_16x16x32_bf16 v[92:95], v[144:147], v[202:205], v[92:95]
	v_mfma_f32_16x16x32_bf16 v[88:91], v[162:165], v[202:205], v[88:91]
	v_mfma_f32_16x16x32_bf16 v[76:79], v[144:147], v[210:213], v[76:79]
	v_mfma_f32_16x16x32_bf16 v[72:75], v[162:165], v[210:213], v[72:75]
	v_mfma_f32_16x16x32_bf16 v[124:127], v[156:159], v[190:193], v[124:127]
	v_mfma_f32_16x16x32_bf16 v[120:123], v[166:169], v[190:193], v[120:123]
	v_mfma_f32_16x16x32_bf16 v[108:111], v[156:159], v[198:201], v[108:111]
	v_mfma_f32_16x16x32_bf16 v[104:107], v[166:169], v[198:201], v[104:107]
	v_mfma_f32_16x16x32_bf16 v[92:95], v[156:159], v[206:209], v[92:95]
	v_mfma_f32_16x16x32_bf16 v[88:91], v[166:169], v[206:209], v[88:91]
	v_mfma_f32_16x16x32_bf16 v[76:79], v[156:159], v[214:217], v[76:79]
	v_mfma_f32_16x16x32_bf16 v[72:75], v[166:169], v[214:217], v[72:75]
	s_setprio 0
	s_setprio 1
	v_mfma_f32_16x16x32_bf16 v[116:119], v[170:173], v[186:189], v[116:119]
	v_mfma_f32_16x16x32_bf16 v[112:115], v[178:181], v[186:189], v[112:115]
	v_mfma_f32_16x16x32_bf16 v[100:103], v[170:173], v[194:197], v[100:103]
	v_mfma_f32_16x16x32_bf16 v[96:99], v[178:181], v[194:197], v[96:99]
	v_mfma_f32_16x16x32_bf16 v[84:87], v[170:173], v[202:205], v[84:87]
	v_mfma_f32_16x16x32_bf16 v[80:83], v[178:181], v[202:205], v[80:83]
	v_mfma_f32_16x16x32_bf16 v[68:71], v[170:173], v[210:213], v[68:71]
	v_mfma_f32_16x16x32_bf16 v[64:67], v[178:181], v[210:213], v[64:67]
	v_mfma_f32_16x16x32_bf16 v[116:119], v[174:177], v[190:193], v[116:119]
	v_mfma_f32_16x16x32_bf16 v[112:115], v[182:185], v[190:193], v[112:115]
	v_mfma_f32_16x16x32_bf16 v[100:103], v[174:177], v[198:201], v[100:103]
	v_mfma_f32_16x16x32_bf16 v[96:99], v[182:185], v[198:201], v[96:99]
	v_mfma_f32_16x16x32_bf16 v[84:87], v[174:177], v[206:209], v[84:87]
	v_mfma_f32_16x16x32_bf16 v[80:83], v[182:185], v[206:209], v[80:83]
	v_mfma_f32_16x16x32_bf16 v[68:71], v[174:177], v[214:217], v[68:71]
	v_mfma_f32_16x16x32_bf16 v[64:67], v[182:185], v[214:217], v[64:67]
	s_setprio 0
	s_barrier
; #define PG8_STAGE(bufoff, gbase, voff) do { _Pragma("unroll") for (int _i = 0; _i < 2; ++_i) \
;         __builtin_amdgcn_global_load_lds((const unsigned*)((const char*)(gbase) + (voff)[_i]), (PG8_LAS unsigned*)(lds + (bufoff) + ldsw + _i * 8192), 16, 0, 0); } while (0)
; #define PG8_LDA(dst, b, h) do { _Pragma("unroll") for (int m = 0; m < 4; ++m) _Pragma("unroll") for (int k = 0; k < 2; ++k) dst[m][k] = *(const PG8_LAS bf16x8*)(lds + PG8_SA(b, h) + aoff + m * 2048 + k * 1024); } while (0)
; #define PG8_MMA(ai, bj, At, Bt) do { __builtin_amdgcn_s_setprio(1); _Pragma("unroll") for (int m = 0; m < 4; ++m) _Pragma("unroll") for (int n = 0; n < 2; ++n) _Pragma("unroll") for (int k = 0; k < 2; ++k) \
;         acc[ai][bj][m][n] = __builtin_amdgcn_mfma_f32_16x16x32_bf16(Bt[n][k], At[m][k], acc[ai][bj][m][n], 0, 0, 0); __builtin_amdgcn_s_setprio(0); } while (0)
; #define PG8_WAIT_V(n) asm volatile("s_waitcnt vmcnt(" #n ")" ::: "memory")
; #define PG8_WAIT_L(n) asm volatile("s_waitcnt lgkmcnt(" #n ")" ::: "memory")
; #define PG8_BAR __builtin_amdgcn_s_barrier()
; #define PG8_SCHED __builtin_amdgcn_sched_barrier(0)
; template <class Epi, class Sched, bool ALIGN_EPI = false, bool SP2 = false>
; __device__ __forceinline__ void gemm_phase(PG8_LAS unsigned char* lds, const Gemm g, const Sched& S, const Epi& E) {
;     ...
;             PG8_LDA(At, 1, 1); PG8_STAGE(PG8_SB(1, 0), b3, voffB); PG8_STAGE(PG8_SB(1, 1), b3 + hstep, voffB); PG8_STAGE(PG8_SA(1, 0), a3, voffA);
;             PG8_WAIT_V(8); PG8_WAIT_L(0); PG8_BAR; PG8_MMA(1, 0, At, B0); PG8_MMA(1, 1, At, B1); PG8_BAR; PG8_SCHED;
	s_add_i32 s36, s62, s38
	v_lshl_add_u64 v[218:219], v[218:219], 0, s[16:17]
	s_mov_b32 m0, s36
	ds_read_b128 v[186:189], v153 offset:49152
	ds_read_b128 v[190:193], v153 offset:50176
	ds_read_b128 v[194:197], v153 offset:51200
	ds_read_b128 v[198:201], v153 offset:52224
	ds_read_b128 v[202:205], v153 offset:53248
	ds_read_b128 v[206:209], v153 offset:54272
	ds_read_b128 v[210:213], v153 offset:55296
	ds_read_b128 v[214:217], v153 offset:56320
	global_load_lds_dwordx4 v[218:219], off
	s_add_i32 m0, s36, 0x2000
	s_add_u32 s34, s34, 0x40080
	v_lshl_add_u64 v[218:219], v[220:221], 0, s[16:17]
	s_addc_u32 s35, s35, 0
	s_add_i32 s36, s63, s38
	global_load_lds_dwordx4 v[218:219], off
	v_lshl_add_u64 v[218:219], s[34:35], 0, v[130:131]
	s_mov_b32 m0, s36
	s_nop 0
	global_load_lds_dwordx4 v[218:219], off
	v_lshl_add_u64 v[218:219], s[34:35], 0, v[134:135]
	s_add_i32 m0, s36, 0x2000
	s_nop 0
	global_load_lds_dwordx4 v[218:219], off
	v_lshl_add_u64 v[218:219], v[222:223], 0, s[16:17]
	s_mov_b32 m0, s45
	s_nop 0
	global_load_lds_dwordx4 v[218:219], off
	v_lshl_add_u64 v[218:219], v[224:225], 0, s[16:17]
	s_mov_b32 m0, s46
	s_nop 0
	global_load_lds_dwordx4 v[218:219], off
	s_waitcnt vmcnt(8)
	s_waitcnt lgkmcnt(0)
	s_barrier
	s_setprio 1
	s_waitcnt lgkmcnt(0)
	v_mfma_f32_16x16x32_bf16 v[60:63], v[144:147], v[186:189], v[60:63]
	v_mfma_f32_16x16x32_bf16 v[56:59], v[162:165], v[186:189], v[56:59]
	v_mfma_f32_16x16x32_bf16 v[44:47], v[144:147], v[194:197], v[44:47]
	v_mfma_f32_16x16x32_bf16 v[40:43], v[162:165], v[194:197], v[40:43]
	v_mfma_f32_16x16x32_bf16 v[28:31], v[144:147], v[202:205], v[28:31]
	v_mfma_f32_16x16x32_bf16 v[24:27], v[162:165], v[202:205], v[24:27]
	v_mfma_f32_16x16x32_bf16 v[12:15], v[144:147], v[210:213], v[12:15]
	v_mfma_f32_16x16x32_bf16 v[8:11], v[162:165], v[210:213], v[8:11]
	v_mfma_f32_16x16x32_bf16 v[60:63], v[156:159], v[190:193], v[60:63]
	v_mfma_f32_16x16x32_bf16 v[56:59], v[166:169], v[190:193], v[56:59]
	v_mfma_f32_16x16x32_bf16 v[44:47], v[156:159], v[198:201], v[44:47]
	v_mfma_f32_16x16x32_bf16 v[40:43], v[166:169], v[198:201], v[40:43]
	v_mfma_f32_16x16x32_bf16 v[28:31], v[156:159], v[206:209], v[28:31]
	v_mfma_f32_16x16x32_bf16 v[24:27], v[166:169], v[206:209], v[24:27]
	v_mfma_f32_16x16x32_bf16 v[12:15], v[156:159], v[214:217], v[12:15]
	v_mfma_f32_16x16x32_bf16 v[8:11], v[166:169], v[214:217], v[8:11]
	s_setprio 0
	s_setprio 1
	v_mfma_f32_16x16x32_bf16 v[52:55], v[170:173], v[186:189], v[52:55]
	v_mfma_f32_16x16x32_bf16 v[48:51], v[178:181], v[186:189], v[48:51]
	v_mfma_f32_16x16x32_bf16 v[36:39], v[170:173], v[194:197], v[36:39]
	v_mfma_f32_16x16x32_bf16 v[32:35], v[178:181], v[194:197], v[32:35]
	v_mfma_f32_16x16x32_bf16 v[20:23], v[170:173], v[202:205], v[20:23]
	v_mfma_f32_16x16x32_bf16 v[16:19], v[178:181], v[202:205], v[16:19]
	v_mfma_f32_16x16x32_bf16 v[4:7], v[170:173], v[210:213], v[4:7]
	v_mfma_f32_16x16x32_bf16 v[0:3], v[178:181], v[210:213], v[0:3]
	v_mfma_f32_16x16x32_bf16 v[52:55], v[174:177], v[190:193], v[52:55]
	v_mfma_f32_16x16x32_bf16 v[48:51], v[182:185], v[190:193], v[48:51]
	v_mfma_f32_16x16x32_bf16 v[36:39], v[174:177], v[198:201], v[36:39]
	v_mfma_f32_16x16x32_bf16 v[32:35], v[182:185], v[198:201], v[32:35]
	v_mfma_f32_16x16x32_bf16 v[20:23], v[174:177], v[206:209], v[20:23]
	v_mfma_f32_16x16x32_bf16 v[16:19], v[182:185], v[206:209], v[16:19]
	v_mfma_f32_16x16x32_bf16 v[4:7], v[174:177], v[214:217], v[4:7]
	v_mfma_f32_16x16x32_bf16 v[0:3], v[182:185], v[214:217], v[0:3]
	s_setprio 0
	s_barrier
	s_add_i32 s55, s55, 2
	s_add_u32 s30, s30, 0x100
	s_addc_u32 s31, s31, 0
	s_add_u32 s53, s53, 0x100
	s_addc_u32 s54, s54, 0
	s_cmp_gt_u32 s55, 13
	s_cbranch_scc0 .LBB0_466
	s_and_b64 vcc, exec, s[18:19]
	s_cbranch_vccz .LBB0_469
	s_barrier

; #define PG8_STAGE(bufoff, gbase, voff) do { _Pragma("unroll") for (int _i = 0; _i < 2; ++_i) \
;         __builtin_amdgcn_global_load_lds((const unsigned*)((const char*)(gbase) + (voff)[_i]), (PG8_LAS unsigned*)(lds + (bufoff) + ldsw + _i * 8192), 16, 0, 0); } while (0)
; #define PG8_LDA(dst, b, h) do { _Pragma("unroll") for (int m = 0; m < 4; ++m) _Pragma("unroll") for (int k = 0; k < 2; ++k) dst[m][k] = *(const PG8_LAS bf16x8*)(lds + PG8_SA(b, h) + aoff + m * 2048 + k * 1024); } while (0)
; #define PG8_LDB(dst, b, h) do { _Pragma("unroll") for (int n = 0; n < 2; ++n) _Pragma("unroll") for (int k = 0; k < 2; ++k) dst[n][k] = *(const PG8_LAS bf16x8*)(lds + PG8_SB(b, h) + boff + n * 2048 + k * 1024); } while (0)
; #define PG8_MMA(ai, bj, At, Bt) do { __builtin_amdgcn_s_setprio(1); _Pragma("unroll") for (int m = 0; m < 4; ++m) _Pragma("unroll") for (int n = 0; n < 2; ++n) _Pragma("unroll") for (int k = 0; k < 2; ++k) \
;         acc[ai][bj][m][n] = __builtin_amdgcn_mfma_f32_16x16x32_bf16(Bt[n][k], At[m][k], acc[ai][bj][m][n], 0, 0, 0); __builtin_amdgcn_s_setprio(0); } while (0)
; #define PG8_WAIT_V(n) asm volatile("s_waitcnt vmcnt(" #n ")" ::: "memory")
; #define PG8_WAIT_L(n) asm volatile("s_waitcnt lgkmcnt(" #n ")" ::: "memory")
; template <class Epi, class Sched, bool ALIGN_EPI = false, bool SP2 = false>
; __device__ __forceinline__ void gemm_phase(PG8_LAS unsigned char* lds, const Gemm g, const Sched& S, const Epi& E) {
;     ...
;             const bool last = (t == nt - 2);
;             const char* a1 = cA + (size_t)(t + 1) * kstep;
;             const char* a2 = last ? nA : cA + (size_t)(t + 2) * kstep; const char* b2 = last ? nB : cB + (size_t)(t + 2) * kstep;
;             const char* a3 = a2 + kstep; const char* b3 = b2 + kstep;
;             if (last && has_next) S.a_ready(nxt);
;             if constexpr (SP2) {
;             PG8_LDB(B0, 0, 0); PG8_LDB(B1, 0, 1); PG8_SCHED; PG8_LDA(At, 0, 0); PG8_STAGE(PG8_SA(1, 1), a1 + hstep, voffA);
;             PG8_WAIT_V(8); PG8_WAIT_L(0); PG8_BAR; PG8_MMA(0, 0, At, B0); PG8_MMA(0, 1, At, B1); PG8_BAR; PG8_SCHED;
;             PG8_LDA(At, 0, 1); PG8_STAGE(PG8_SB(0, 0), b2, voffB); PG8_STAGE(PG8_SB(0, 1), b2 + hstep, voffB); PG8_STAGE(PG8_SA(0, 0), a2, voffA);
;             PG8_WAIT_V(8); PG8_WAIT_L(0); PG8_BAR; PG8_MMA(1, 0, At, B0); PG8_MMA(1, 1, At, B1); PG8_BAR; PG8_SCHED;
.LBB0_561:
	ds_read_b128 v[152:155], v149
	ds_read_b128 v[156:159], v149 offset:1024
	ds_read_b128 v[162:165], v149 offset:2048
	ds_read_b128 v[166:169], v149 offset:3072
	ds_read_b128 v[170:173], v150
	ds_read_b128 v[174:177], v150 offset:1024
	ds_read_b128 v[178:181], v150 offset:2048
	ds_read_b128 v[182:185], v150 offset:3072
	s_add_u32 s34, s30, 0xfffc0080
	s_addc_u32 s35, s31, -1
	s_cmp_eq_u32 s65, 12
	s_cselect_b32 s37, s23, s35
	s_cselect_b32 s36, s61, s34
	s_cselect_b32 s35, s21, s64
	s_cselect_b32 s34, s62, s63
	v_lshl_add_u64 v[144:145], s[30:31], 0, v[136:137]
	s_add_i32 m0, s29, 0xc000
	ds_read_b128 v[186:189], v151
	ds_read_b128 v[190:193], v151 offset:1024
	ds_read_b128 v[194:197], v151 offset:2048
	ds_read_b128 v[198:201], v151 offset:3072
	ds_read_b128 v[202:205], v151 offset:4096
	ds_read_b128 v[206:209], v151 offset:5120
	ds_read_b128 v[210:213], v151 offset:6144
	ds_read_b128 v[214:217], v151 offset:7168
	global_load_lds_dwordx4 v[144:145], off
	v_lshl_add_u64 v[144:145], s[30:31], 0, v[138:139]
	s_add_i32 m0, s29, 0xe000
	s_nop 0
	global_load_lds_dwordx4 v[144:145], off
	s_waitcnt vmcnt(8)
	s_waitcnt lgkmcnt(0)
	s_barrier
	s_setprio 1
	s_waitcnt lgkmcnt(0)
	v_mfma_f32_16x16x32_bf16 v[124:127], v[152:155], v[186:189], v[124:127]
	v_mfma_f32_16x16x32_bf16 v[120:123], v[162:165], v[186:189], v[120:123]
	v_mfma_f32_16x16x32_bf16 v[108:111], v[152:155], v[194:197], v[108:111]
	v_mfma_f32_16x16x32_bf16 v[104:107], v[162:165], v[194:197], v[104:107]
	v_mfma_f32_16x16x32_bf16 v[92:95], v[152:155], v[202:205], v[92:95]
	v_mfma_f32_16x16x32_bf16 v[88:91], v[162:165], v[202:205], v[88:91]
	v_mfma_f32_16x16x32_bf16 v[76:79], v[152:155], v[210:213], v[76:79]
	v_mfma_f32_16x16x32_bf16 v[72:75], v[162:165], v[210:213], v[72:75]
	v_mfma_f32_16x16x32_bf16 v[124:127], v[156:159], v[190:193], v[124:127]
	v_mfma_f32_16x16x32_bf16 v[120:123], v[166:169], v[190:193], v[120:123]
	v_mfma_f32_16x16x32_bf16 v[108:111], v[156:159], v[198:201], v[108:111]
	v_mfma_f32_16x16x32_bf16 v[104:107], v[166:169], v[198:201], v[104:107]
	v_mfma_f32_16x16x32_bf16 v[92:95], v[156:159], v[206:209], v[92:95]
	v_mfma_f32_16x16x32_bf16 v[88:91], v[166:169], v[206:209], v[88:91]
	v_mfma_f32_16x16x32_bf16 v[76:79], v[156:159], v[214:217], v[76:79]
	v_mfma_f32_16x16x32_bf16 v[72:75], v[166:169], v[214:217], v[72:75]
	s_setprio 0
	s_setprio 1
	v_mfma_f32_16x16x32_bf16 v[116:119], v[170:173], v[186:189], v[116:119]
	v_mfma_f32_16x16x32_bf16 v[112:115], v[178:181], v[186:189], v[112:115]
	v_mfma_f32_16x16x32_bf16 v[100:103], v[170:173], v[194:197], v[100:103]
	v_mfma_f32_16x16x32_bf16 v[96:99], v[178:181], v[194:197], v[96:99]
	v_mfma_f32_16x16x32_bf16 v[84:87], v[170:173], v[202:205], v[84:87]
	v_mfma_f32_16x16x32_bf16 v[80:83], v[178:181], v[202:205], v[80:83]
	v_mfma_f32_16x16x32_bf16 v[68:71], v[170:173], v[210:213], v[68:71]
	v_mfma_f32_16x16x32_bf16 v[64:67], v[178:181], v[210:213], v[64:67]
	v_mfma_f32_16x16x32_bf16 v[116:119], v[174:177], v[190:193], v[116:119]
	v_mfma_f32_16x16x32_bf16 v[112:115], v[182:185], v[190:193], v[112:115]
	v_mfma_f32_16x16x32_bf16 v[100:103], v[174:177], v[198:201], v[100:103]
	v_mfma_f32_16x16x32_bf16 v[96:99], v[182:185], v[198:201], v[96:99]
	v_mfma_f32_16x16x32_bf16 v[84:87], v[174:177], v[206:209], v[84:87]
	v_mfma_f32_16x16x32_bf16 v[80:83], v[182:185], v[206:209], v[80:83]
	v_mfma_f32_16x16x32_bf16 v[68:71], v[174:177], v[214:217], v[68:71]
	v_mfma_f32_16x16x32_bf16 v[64:67], v[182:185], v[214:217], v[64:67]
	s_setprio 0
	s_barrier
	s_add_i32 s66, s50, s41
	v_lshl_add_u64 v[144:145], s[34:35], 0, v[130:131]
	s_mov_b32 m0, s66
	ds_read_b128 v[186:189], v151 offset:16384
	ds_read_b128 v[190:193], v151 offset:17408
	ds_read_b128 v[194:197], v151 offset:18432
	ds_read_b128 v[198:201], v151 offset:19456
	ds_read_b128 v[202:205], v151 offset:20480
	ds_read_b128 v[206:209], v151 offset:21504
	ds_read_b128 v[210:213], v151 offset:22528
	ds_read_b128 v[214:217], v151 offset:23552
	global_load_lds_dwordx4 v[144:145], off
	s_add_i32 m0, s66, 0x2000
	s_add_u32 s66, s34, 0x40000
	v_lshl_add_u64 v[218:219], s[34:35], 0, v[134:135]
	s_addc_u32 s67, s35, 0
	s_add_i32 s68, s51, s41
	global_load_lds_dwordx4 v[218:219], off
	v_lshl_add_u64 v[220:221], s[66:67], 0, v[130:131]
	s_mov_b32 m0, s68
	s_nop 0
	global_load_lds_dwordx4 v[220:221], off
	v_lshl_add_u64 v[220:221], s[66:67], 0, v[134:135]
	s_add_i32 m0, s68, 0x2000
	s_nop 0
	global_load_lds_dwordx4 v[220:221], off
	s_nop 0
	s_waitcnt vmcnt(6)
	s_waitcnt lgkmcnt(0)
	s_barrier
; #define PG8_STAGE(bufoff, gbase, voff) do { _Pragma("unroll") for (int _i = 0; _i < 2; ++_i) \
;         __builtin_amdgcn_global_load_lds((const unsigned*)((const char*)(gbase) + (voff)[_i]), (PG8_LAS unsigned*)(lds + (bufoff) + ldsw + _i * 8192), 16, 0, 0); } while (0)
; #define PG8_LDA(dst, b, h) do { _Pragma("unroll") for (int m = 0; m < 4; ++m) _Pragma("unroll") for (int k = 0; k < 2; ++k) dst[m][k] = *(const PG8_LAS bf16x8*)(lds + PG8_SA(b, h) + aoff + m * 2048 + k * 1024); } while (0)
; #define PG8_LDB(dst, b, h) do { _Pragma("unroll") for (int n = 0; n < 2; ++n) _Pragma("unroll") for (int k = 0; k < 2; ++k) dst[n][k] = *(const PG8_LAS bf16x8*)(lds + PG8_SB(b, h) + boff + n * 2048 + k * 1024); } while (0)
; #define PG8_MMA(ai, bj, At, Bt) do { __builtin_amdgcn_s_setprio(1); _Pragma("unroll") for (int m = 0; m < 4; ++m) _Pragma("unroll") for (int n = 0; n < 2; ++n) _Pragma("unroll") for (int k = 0; k < 2; ++k) \
;         acc[ai][bj][m][n] = __builtin_amdgcn_mfma_f32_16x16x32_bf16(Bt[n][k], At[m][k], acc[ai][bj][m][n], 0, 0, 0); __builtin_amdgcn_s_setprio(0); } while (0)
; #define PG8_WAIT_V(n) asm volatile("s_waitcnt vmcnt(" #n ")" ::: "memory")
; #define PG8_WAIT_L(n) asm volatile("s_waitcnt lgkmcnt(" #n ")" ::: "memory")
; #define PG8_BAR __builtin_amdgcn_s_barrier()
; #define PG8_SCHED __builtin_amdgcn_sched_barrier(0)
; template <class Epi, class Sched, bool ALIGN_EPI = false, bool SP2 = false>
; __device__ __forceinline__ void gemm_phase(PG8_LAS unsigned char* lds, const Gemm g, const Sched& S, const Epi& E) {
;     ...
;             PG8_WAIT_V(8); PG8_WAIT_L(0); PG8_BAR; PG8_MMA(0, 0, At, B0); PG8_MMA(0, 1, At, B1); PG8_BAR; PG8_SCHED;
;             PG8_LDA(At, 0, 1); PG8_STAGE(PG8_SB(0, 0), b2, voffB); PG8_STAGE(PG8_SB(0, 1), b2 + hstep, voffB); PG8_STAGE(PG8_SA(0, 0), a2, voffA);
;             PG8_WAIT_V(8); PG8_WAIT_L(0); PG8_BAR; PG8_MMA(1, 0, At, B0); PG8_MMA(1, 1, At, B1); PG8_BAR; PG8_SCHED;
;             PG8_LDB(B0, 1, 0); PG8_LDB(B1, 1, 1); PG8_SCHED; PG8_LDA(At, 1, 0); PG8_STAGE(PG8_SA(0, 1), a2 + hstep, voffA);
;             PG8_WAIT_V(8); PG8_WAIT_L(0); PG8_BAR; PG8_MMA(0, 0, At, B0); PG8_MMA(0, 1, At, B1); PG8_BAR; PG8_SCHED;
	s_setprio 1
	s_waitcnt lgkmcnt(0)
	v_mfma_f32_16x16x32_bf16 v[60:63], v[152:155], v[186:189], v[60:63]
	v_mfma_f32_16x16x32_bf16 v[56:59], v[162:165], v[186:189], v[56:59]
	v_mfma_f32_16x16x32_bf16 v[44:47], v[152:155], v[194:197], v[44:47]
	v_mfma_f32_16x16x32_bf16 v[40:43], v[162:165], v[194:197], v[40:43]
	v_mfma_f32_16x16x32_bf16 v[28:31], v[152:155], v[202:205], v[28:31]
	v_mfma_f32_16x16x32_bf16 v[24:27], v[162:165], v[202:205], v[24:27]
	v_mfma_f32_16x16x32_bf16 v[12:15], v[152:155], v[210:213], v[12:15]
	v_mfma_f32_16x16x32_bf16 v[8:11], v[162:165], v[210:213], v[8:11]
	v_mfma_f32_16x16x32_bf16 v[60:63], v[156:159], v[190:193], v[60:63]
	v_mfma_f32_16x16x32_bf16 v[56:59], v[166:169], v[190:193], v[56:59]
	v_mfma_f32_16x16x32_bf16 v[44:47], v[156:159], v[198:201], v[44:47]
	v_mfma_f32_16x16x32_bf16 v[40:43], v[166:169], v[198:201], v[40:43]
	v_mfma_f32_16x16x32_bf16 v[28:31], v[156:159], v[206:209], v[28:31]
	v_mfma_f32_16x16x32_bf16 v[24:27], v[166:169], v[206:209], v[24:27]
	v_mfma_f32_16x16x32_bf16 v[12:15], v[156:159], v[214:217], v[12:15]
	v_mfma_f32_16x16x32_bf16 v[8:11], v[166:169], v[214:217], v[8:11]
	s_setprio 0
	s_setprio 1
	v_mfma_f32_16x16x32_bf16 v[52:55], v[170:173], v[186:189], v[52:55]
	v_mfma_f32_16x16x32_bf16 v[48:51], v[178:181], v[186:189], v[48:51]
	v_mfma_f32_16x16x32_bf16 v[36:39], v[170:173], v[194:197], v[36:39]
	v_mfma_f32_16x16x32_bf16 v[32:35], v[178:181], v[194:197], v[32:35]
	v_mfma_f32_16x16x32_bf16 v[20:23], v[170:173], v[202:205], v[20:23]
	v_mfma_f32_16x16x32_bf16 v[16:19], v[178:181], v[202:205], v[16:19]
	v_mfma_f32_16x16x32_bf16 v[4:7], v[170:173], v[210:213], v[4:7]
	v_mfma_f32_16x16x32_bf16 v[0:3], v[178:181], v[210:213], v[0:3]
	v_mfma_f32_16x16x32_bf16 v[52:55], v[174:177], v[190:193], v[52:55]
	v_mfma_f32_16x16x32_bf16 v[48:51], v[182:185], v[190:193], v[48:51]
	v_mfma_f32_16x16x32_bf16 v[36:39], v[174:177], v[198:201], v[36:39]
	v_mfma_f32_16x16x32_bf16 v[32:35], v[182:185], v[198:201], v[32:35]
	v_mfma_f32_16x16x32_bf16 v[20:23], v[174:177], v[206:209], v[20:23]
	v_mfma_f32_16x16x32_bf16 v[16:19], v[182:185], v[206:209], v[16:19]
	v_mfma_f32_16x16x32_bf16 v[4:7], v[174:177], v[214:217], v[4:7]
	v_mfma_f32_16x16x32_bf16 v[0:3], v[182:185], v[214:217], v[0:3]
	s_setprio 0
	s_barrier
	s_add_i32 s66, 0, 0x18000
	v_add_u32_e32 v161, s66, v147
	s_add_i32 s67, 0, 0x1c000
	ds_read_b128 v[152:155], v161
	ds_read_b128 v[156:159], v161 offset:1024
	ds_read_b128 v[162:165], v161 offset:2048
	ds_read_b128 v[166:169], v161 offset:3072
	v_add_u32_e32 v161, s67, v147
	ds_read_b128 v[170:173], v161
	ds_read_b128 v[174:177], v161 offset:1024
	ds_read_b128 v[178:181], v161 offset:2048
	ds_read_b128 v[182:185], v161 offset:3072
	v_lshl_add_u64 v[222:223], s[36:37], 0, v[132:133]
	v_lshl_add_u64 v[220:221], s[36:37], 0, v[128:129]
	s_mov_b32 m0, s29
	s_nop 0
	global_load_lds_dwordx4 v[220:221], off
	s_mov_b32 m0, s43
	s_nop 0
	global_load_lds_dwordx4 v[222:223], off
	s_add_u32 s36, s36, 0x40000
	s_addc_u32 s37, s37, 0
	s_mov_b32 m0, s44
	v_lshl_add_u64 v[224:225], s[36:37], 0, v[128:129]
	ds_read_b128 v[186:189], v151 offset:32768
	ds_read_b128 v[190:193], v151 offset:33792
	ds_read_b128 v[194:197], v151 offset:34816
	ds_read_b128 v[198:201], v151 offset:35840
	ds_read_b128 v[202:205], v151 offset:36864
	ds_read_b128 v[206:209], v151 offset:37888
	ds_read_b128 v[210:213], v151 offset:38912
	ds_read_b128 v[214:217], v151 offset:39936
	global_load_lds_dwordx4 v[224:225], off
	v_lshl_add_u64 v[224:225], s[36:37], 0, v[132:133]
	s_mov_b32 m0, s45
	s_nop 0
	global_load_lds_dwordx4 v[224:225], off
	s_waitcnt vmcnt(8)
	s_waitcnt lgkmcnt(0)
	s_barrier
	s_setprio 1
	s_waitcnt lgkmcnt(0)
	v_mfma_f32_16x16x32_bf16 v[124:127], v[152:155], v[186:189], v[124:127]
	v_mfma_f32_16x16x32_bf16 v[120:123], v[162:165], v[186:189], v[120:123]
	v_mfma_f32_16x16x32_bf16 v[108:111], v[152:155], v[194:197], v[108:111]
	v_mfma_f32_16x16x32_bf16 v[104:107], v[162:165], v[194:197], v[104:107]
	v_mfma_f32_16x16x32_bf16 v[92:95], v[152:155], v[202:205], v[92:95]
	v_mfma_f32_16x16x32_bf16 v[88:91], v[162:165], v[202:205], v[88:91]
	v_mfma_f32_16x16x32_bf16 v[76:79], v[152:155], v[210:213], v[76:79]
	v_mfma_f32_16x16x32_bf16 v[72:75], v[162:165], v[210:213], v[72:75]
	v_mfma_f32_16x16x32_bf16 v[124:127], v[156:159], v[190:193], v[124:127]
	v_mfma_f32_16x16x32_bf16 v[120:123], v[166:169], v[190:193], v[120:123]
	v_mfma_f32_16x16x32_bf16 v[108:111], v[156:159], v[198:201], v[108:111]
	v_mfma_f32_16x16x32_bf16 v[104:107], v[166:169], v[198:201], v[104:107]
	v_mfma_f32_16x16x32_bf16 v[92:95], v[156:159], v[206:209], v[92:95]
	v_mfma_f32_16x16x32_bf16 v[88:91], v[166:169], v[206:209], v[88:91]
	v_mfma_f32_16x16x32_bf16 v[76:79], v[156:159], v[214:217], v[76:79]
	v_mfma_f32_16x16x32_bf16 v[72:75], v[166:169], v[214:217], v[72:75]
	s_setprio 0
	s_setprio 1
	v_mfma_f32_16x16x32_bf16 v[116:119], v[170:173], v[186:189], v[116:119]
	v_mfma_f32_16x16x32_bf16 v[112:115], v[178:181], v[186:189], v[112:115]
	v_mfma_f32_16x16x32_bf16 v[100:103], v[170:173], v[194:197], v[100:103]
	v_mfma_f32_16x16x32_bf16 v[96:99], v[178:181], v[194:197], v[96:99]
	v_mfma_f32_16x16x32_bf16 v[84:87], v[170:173], v[202:205], v[84:87]
	v_mfma_f32_16x16x32_bf16 v[80:83], v[178:181], v[202:205], v[80:83]
	v_mfma_f32_16x16x32_bf16 v[68:71], v[170:173], v[210:213], v[68:71]
	v_mfma_f32_16x16x32_bf16 v[64:67], v[178:181], v[210:213], v[64:67]
	v_mfma_f32_16x16x32_bf16 v[116:119], v[174:177], v[190:193], v[116:119]
	v_mfma_f32_16x16x32_bf16 v[112:115], v[182:185], v[190:193], v[112:115]
	v_mfma_f32_16x16x32_bf16 v[100:103], v[174:177], v[198:201], v[100:103]
	v_mfma_f32_16x16x32_bf16 v[96:99], v[182:185], v[198:201], v[96:99]
	v_mfma_f32_16x16x32_bf16 v[84:87], v[174:177], v[206:209], v[84:87]
	v_mfma_f32_16x16x32_bf16 v[80:83], v[182:185], v[206:209], v[80:83]
	v_mfma_f32_16x16x32_bf16 v[68:71], v[174:177], v[214:217], v[68:71]
	v_mfma_f32_16x16x32_bf16 v[64:67], v[182:185], v[214:217], v[64:67]
	s_setprio 0
	s_barrier
; #define PG8_STAGE(bufoff, gbase, voff) do { _Pragma("unroll") for (int _i = 0; _i < 2; ++_i) \
;         __builtin_amdgcn_global_load_lds((const unsigned*)((const char*)(gbase) + (voff)[_i]), (PG8_LAS unsigned*)(lds + (bufoff) + ldsw + _i * 8192), 16, 0, 0); } while (0)
; #define PG8_LDA(dst, b, h) do { _Pragma("unroll") for (int m = 0; m < 4; ++m) _Pragma("unroll") for (int k = 0; k < 2; ++k) dst[m][k] = *(const PG8_LAS bf16x8*)(lds + PG8_SA(b, h) + aoff + m * 2048 + k * 1024); } while (0)
; #define PG8_MMA(ai, bj, At, Bt) do { __builtin_amdgcn_s_setprio(1); _Pragma("unroll") for (int m = 0; m < 4; ++m) _Pragma("unroll") for (int n = 0; n < 2; ++n) _Pragma("unroll") for (int k = 0; k < 2; ++k) \
;         acc[ai][bj][m][n] = __builtin_amdgcn_mfma_f32_16x16x32_bf16(Bt[n][k], At[m][k], acc[ai][bj][m][n], 0, 0, 0); __builtin_amdgcn_s_setprio(0); } while (0)
; #define PG8_WAIT_V(n) asm volatile("s_waitcnt vmcnt(" #n ")" ::: "memory")
; #define PG8_WAIT_L(n) asm volatile("s_waitcnt lgkmcnt(" #n ")" ::: "memory")
; #define PG8_BAR __builtin_amdgcn_s_barrier()
; #define PG8_SCHED __builtin_amdgcn_sched_barrier(0)
; template <class Epi, class Sched, bool ALIGN_EPI = false, bool SP2 = false>
; __device__ __forceinline__ void gemm_phase(PG8_LAS unsigned char* lds, const Gemm g, const Sched& S, const Epi& E) {
;     ...
;             PG8_LDA(At, 1, 1); PG8_STAGE(PG8_SB(1, 0), b3, voffB); PG8_STAGE(PG8_SB(1, 1), b3 + hstep, voffB); PG8_STAGE(PG8_SA(1, 0), a3, voffA);
;             PG8_WAIT_V(8); PG8_WAIT_L(0); PG8_BAR; PG8_MMA(1, 0, At, B0); PG8_MMA(1, 1, At, B1); PG8_BAR; PG8_SCHED;
	s_add_i32 s36, s66, s41
	v_lshl_add_u64 v[144:145], v[144:145], 0, s[8:9]
	s_mov_b32 m0, s36
	ds_read_b128 v[186:189], v151 offset:49152
	ds_read_b128 v[190:193], v151 offset:50176
	ds_read_b128 v[194:197], v151 offset:51200
	ds_read_b128 v[198:201], v151 offset:52224
	ds_read_b128 v[202:205], v151 offset:53248
	ds_read_b128 v[206:209], v151 offset:54272
	ds_read_b128 v[210:213], v151 offset:55296
	ds_read_b128 v[214:217], v151 offset:56320
	global_load_lds_dwordx4 v[144:145], off
	s_add_i32 m0, s36, 0x2000
	s_add_u32 s34, s34, 0x40080
	v_lshl_add_u64 v[144:145], v[218:219], 0, s[8:9]
	s_addc_u32 s35, s35, 0
	s_add_i32 s36, s67, s41
	global_load_lds_dwordx4 v[144:145], off
	v_lshl_add_u64 v[144:145], s[34:35], 0, v[130:131]
	s_mov_b32 m0, s36
	s_nop 0
	global_load_lds_dwordx4 v[144:145], off
	v_lshl_add_u64 v[144:145], s[34:35], 0, v[134:135]
	s_add_i32 m0, s36, 0x2000
	s_nop 0
	global_load_lds_dwordx4 v[144:145], off
	v_lshl_add_u64 v[144:145], v[220:221], 0, s[8:9]
	s_mov_b32 m0, s47
	s_nop 0
	global_load_lds_dwordx4 v[144:145], off
	v_lshl_add_u64 v[144:145], v[222:223], 0, s[8:9]
	s_mov_b32 m0, s48
	s_nop 0
	global_load_lds_dwordx4 v[144:145], off
	s_waitcnt vmcnt(8)
	s_waitcnt lgkmcnt(0)
	s_barrier
	s_setprio 1
	s_waitcnt lgkmcnt(0)
	v_mfma_f32_16x16x32_bf16 v[60:63], v[152:155], v[186:189], v[60:63]
	v_mfma_f32_16x16x32_bf16 v[56:59], v[162:165], v[186:189], v[56:59]
	v_mfma_f32_16x16x32_bf16 v[44:47], v[152:155], v[194:197], v[44:47]
	v_mfma_f32_16x16x32_bf16 v[40:43], v[162:165], v[194:197], v[40:43]
	v_mfma_f32_16x16x32_bf16 v[28:31], v[152:155], v[202:205], v[28:31]
	v_mfma_f32_16x16x32_bf16 v[24:27], v[162:165], v[202:205], v[24:27]
	v_mfma_f32_16x16x32_bf16 v[12:15], v[152:155], v[210:213], v[12:15]
	v_mfma_f32_16x16x32_bf16 v[8:11], v[162:165], v[210:213], v[8:11]
	v_mfma_f32_16x16x32_bf16 v[60:63], v[156:159], v[190:193], v[60:63]
	v_mfma_f32_16x16x32_bf16 v[56:59], v[166:169], v[190:193], v[56:59]
	v_mfma_f32_16x16x32_bf16 v[44:47], v[156:159], v[198:201], v[44:47]
	v_mfma_f32_16x16x32_bf16 v[40:43], v[166:169], v[198:201], v[40:43]
	v_mfma_f32_16x16x32_bf16 v[28:31], v[156:159], v[206:209], v[28:31]
	v_mfma_f32_16x16x32_bf16 v[24:27], v[166:169], v[206:209], v[24:27]
	v_mfma_f32_16x16x32_bf16 v[12:15], v[156:159], v[214:217], v[12:15]
	v_mfma_f32_16x16x32_bf16 v[8:11], v[166:169], v[214:217], v[8:11]
	s_setprio 0
	s_setprio 1
	v_mfma_f32_16x16x32_bf16 v[52:55], v[170:173], v[186:189], v[52:55]
	v_mfma_f32_16x16x32_bf16 v[48:51], v[178:181], v[186:189], v[48:51]
	v_mfma_f32_16x16x32_bf16 v[36:39], v[170:173], v[194:197], v[36:39]
	v_mfma_f32_16x16x32_bf16 v[32:35], v[178:181], v[194:197], v[32:35]
	v_mfma_f32_16x16x32_bf16 v[20:23], v[170:173], v[202:205], v[20:23]
	v_mfma_f32_16x16x32_bf16 v[16:19], v[178:181], v[202:205], v[16:19]
	v_mfma_f32_16x16x32_bf16 v[4:7], v[170:173], v[210:213], v[4:7]
	v_mfma_f32_16x16x32_bf16 v[0:3], v[178:181], v[210:213], v[0:3]
	v_mfma_f32_16x16x32_bf16 v[52:55], v[174:177], v[190:193], v[52:55]
	v_mfma_f32_16x16x32_bf16 v[48:51], v[182:185], v[190:193], v[48:51]
	v_mfma_f32_16x16x32_bf16 v[36:39], v[174:177], v[198:201], v[36:39]
	v_mfma_f32_16x16x32_bf16 v[32:35], v[182:185], v[198:201], v[32:35]
	v_mfma_f32_16x16x32_bf16 v[20:23], v[174:177], v[206:209], v[20:23]
	v_mfma_f32_16x16x32_bf16 v[16:19], v[182:185], v[206:209], v[16:19]
	v_mfma_f32_16x16x32_bf16 v[4:7], v[174:177], v[214:217], v[4:7]
	v_mfma_f32_16x16x32_bf16 v[0:3], v[182:185], v[214:217], v[0:3]
	s_setprio 0
	s_barrier
	s_add_i32 s65, s65, 2
	s_add_u32 s30, s30, 0x100
	s_addc_u32 s31, s31, 0
	s_add_u32 s63, s63, 0x100
	s_addc_u32 s64, s64, 0
	s_cmp_gt_u32 s65, 13
	s_cbranch_scc0 .LBB0_561
	s_and_b64 vcc, exec, s[10:11]
	s_cbranch_vccz .LBB0_564
	s_barrier

; #define PG8_STAGE(bufoff, gbase, voff) do { _Pragma("unroll") for (int _i = 0; _i < 2; ++_i) \
;         __builtin_amdgcn_global_load_lds((const unsigned*)((const char*)(gbase) + (voff)[_i]), (PG8_LAS unsigned*)(lds + (bufoff) + ldsw + _i * 8192), 16, 0, 0); } while (0)
; #define PG8_LDA(dst, b, h) do { _Pragma("unroll") for (int m = 0; m < 4; ++m) _Pragma("unroll") for (int k = 0; k < 2; ++k) dst[m][k] = *(const PG8_LAS bf16x8*)(lds + PG8_SA(b, h) + aoff + m * 2048 + k * 1024); } while (0)
; #define PG8_LDB(dst, b, h) do { _Pragma("unroll") for (int n = 0; n < 2; ++n) _Pragma("unroll") for (int k = 0; k < 2; ++k) dst[n][k] = *(const PG8_LAS bf16x8*)(lds + PG8_SB(b, h) + boff + n * 2048 + k * 1024); } while (0)
; #define PG8_MMA(ai, bj, At, Bt) do { __builtin_amdgcn_s_setprio(1); _Pragma("unroll") for (int m = 0; m < 4; ++m) _Pragma("unroll") for (int n = 0; n < 2; ++n) _Pragma("unroll") for (int k = 0; k < 2; ++k) \
;         acc[ai][bj][m][n] = __builtin_amdgcn_mfma_f32_16x16x32_bf16(Bt[n][k], At[m][k], acc[ai][bj][m][n], 0, 0, 0); __builtin_amdgcn_s_setprio(0); } while (0)
; #define PG8_WAIT_V(n) asm volatile("s_waitcnt vmcnt(" #n ")" ::: "memory")
; #define PG8_WAIT_L(n) asm volatile("s_waitcnt lgkmcnt(" #n ")" ::: "memory")
; template <class Epi, class Sched, bool ALIGN_EPI = false, bool SP2 = false>
; __device__ __forceinline__ void gemm_phase(PG8_LAS unsigned char* lds, const Gemm g, const Sched& S, const Epi& E) {
;     ...
;             const bool last = (t == nt - 2);
;             const char* a1 = cA + (size_t)(t + 1) * kstep;
;             const char* a2 = last ? nA : cA + (size_t)(t + 2) * kstep; const char* b2 = last ? nB : cB + (size_t)(t + 2) * kstep;
;             const char* a3 = a2 + kstep; const char* b3 = b2 + kstep;
;             if (last && has_next) S.a_ready(nxt);
;             if constexpr (SP2) {
;             PG8_LDB(B0, 0, 0); PG8_LDB(B1, 0, 1); PG8_SCHED; PG8_LDA(At, 0, 0); PG8_STAGE(PG8_SA(1, 1), a1 + hstep, voffA);
;             PG8_WAIT_V(8); PG8_WAIT_L(0); PG8_BAR; PG8_MMA(0, 0, At, B0); PG8_MMA(0, 1, At, B1); PG8_BAR; PG8_SCHED;
;             PG8_LDA(At, 0, 1); PG8_STAGE(PG8_SB(0, 0), b2, voffB); PG8_STAGE(PG8_SB(0, 1), b2 + hstep, voffB); PG8_STAGE(PG8_SA(0, 0), a2, voffA);
;             PG8_WAIT_V(8); PG8_WAIT_L(0); PG8_BAR; PG8_MMA(1, 0, At, B0); PG8_MMA(1, 1, At, B1); PG8_BAR; PG8_SCHED;
.LBB0_642:
	ds_read_b128 v[144:147], v192
	ds_read_b128 v[148:151], v192 offset:1024
	ds_read_b128 v[152:155], v192 offset:2048
	ds_read_b128 v[156:159], v192 offset:3072
	ds_read_b128 v[160:163], v193
	ds_read_b128 v[164:167], v193 offset:1024
	ds_read_b128 v[168:171], v193 offset:2048
	ds_read_b128 v[208:211], v193 offset:3072
	s_add_u32 s38, s36, 0xfff00080
	s_addc_u32 s39, s37, -1
	s_cmp_eq_u32 s65, 60
	s_cselect_b32 s41, s13, s39
	s_cselect_b32 s40, s27, s38
	s_cselect_b32 s39, s25, s64
	s_cselect_b32 s38, s35, s63
	v_lshl_add_u64 v[244:245], s[36:37], 0, v[138:139]
	s_add_i32 m0, s44, 0xc000
	ds_read_b128 v[212:215], v194
	ds_read_b128 v[216:219], v194 offset:1024
	ds_read_b128 v[220:223], v194 offset:2048
	ds_read_b128 v[224:227], v194 offset:3072
	ds_read_b128 v[228:231], v194 offset:4096
	ds_read_b128 v[232:235], v194 offset:5120
	ds_read_b128 v[236:239], v194 offset:6144
	ds_read_b128 v[240:243], v194 offset:7168
	global_load_lds_dwordx4 v[244:245], off
	v_lshl_add_u64 v[244:245], s[36:37], 0, v[140:141]
	s_add_i32 m0, s44, 0xe000
	s_nop 0
	global_load_lds_dwordx4 v[244:245], off
	s_waitcnt vmcnt(8)
	s_waitcnt lgkmcnt(0)
	s_barrier
	s_setprio 1
	s_waitcnt lgkmcnt(0)
	v_mfma_f32_16x16x32_bf16 v[124:127], v[144:147], v[212:215], v[124:127]
	v_mfma_f32_16x16x32_bf16 v[120:123], v[152:155], v[212:215], v[120:123]
	v_mfma_f32_16x16x32_bf16 v[108:111], v[144:147], v[220:223], v[108:111]
	v_mfma_f32_16x16x32_bf16 v[104:107], v[152:155], v[220:223], v[104:107]
	v_mfma_f32_16x16x32_bf16 v[92:95], v[144:147], v[228:231], v[92:95]
	v_mfma_f32_16x16x32_bf16 v[88:91], v[152:155], v[228:231], v[88:91]
	v_mfma_f32_16x16x32_bf16 v[76:79], v[144:147], v[236:239], v[76:79]
	v_mfma_f32_16x16x32_bf16 v[72:75], v[152:155], v[236:239], v[72:75]
	v_mfma_f32_16x16x32_bf16 v[124:127], v[148:151], v[216:219], v[124:127]
	v_mfma_f32_16x16x32_bf16 v[120:123], v[156:159], v[216:219], v[120:123]
	v_mfma_f32_16x16x32_bf16 v[108:111], v[148:151], v[224:227], v[108:111]
	v_mfma_f32_16x16x32_bf16 v[104:107], v[156:159], v[224:227], v[104:107]
	v_mfma_f32_16x16x32_bf16 v[92:95], v[148:151], v[232:235], v[92:95]
	v_mfma_f32_16x16x32_bf16 v[88:91], v[156:159], v[232:235], v[88:91]
	v_mfma_f32_16x16x32_bf16 v[76:79], v[148:151], v[240:243], v[76:79]
	v_mfma_f32_16x16x32_bf16 v[72:75], v[156:159], v[240:243], v[72:75]
	s_setprio 0
	s_setprio 1
	v_mfma_f32_16x16x32_bf16 v[116:119], v[160:163], v[212:215], v[116:119]
	v_mfma_f32_16x16x32_bf16 v[112:115], v[168:171], v[212:215], v[112:115]
	v_mfma_f32_16x16x32_bf16 v[100:103], v[160:163], v[220:223], v[100:103]
	v_mfma_f32_16x16x32_bf16 v[96:99], v[168:171], v[220:223], v[96:99]
	v_mfma_f32_16x16x32_bf16 v[84:87], v[160:163], v[228:231], v[84:87]
	v_mfma_f32_16x16x32_bf16 v[80:83], v[168:171], v[228:231], v[80:83]
	v_mfma_f32_16x16x32_bf16 v[68:71], v[160:163], v[236:239], v[68:71]
	v_mfma_f32_16x16x32_bf16 v[64:67], v[168:171], v[236:239], v[64:67]
	v_mfma_f32_16x16x32_bf16 v[116:119], v[164:167], v[216:219], v[116:119]
	v_mfma_f32_16x16x32_bf16 v[112:115], v[208:211], v[216:219], v[112:115]
	v_mfma_f32_16x16x32_bf16 v[100:103], v[164:167], v[224:227], v[100:103]
	v_mfma_f32_16x16x32_bf16 v[96:99], v[208:211], v[224:227], v[96:99]
	v_mfma_f32_16x16x32_bf16 v[84:87], v[164:167], v[232:235], v[84:87]
	v_mfma_f32_16x16x32_bf16 v[80:83], v[208:211], v[232:235], v[80:83]
	v_mfma_f32_16x16x32_bf16 v[68:71], v[164:167], v[240:243], v[68:71]
	v_mfma_f32_16x16x32_bf16 v[64:67], v[208:211], v[240:243], v[64:67]
	s_setprio 0
	s_barrier
	s_add_i32 s66, s55, s43
	v_lshl_add_u64 v[244:245], s[38:39], 0, v[130:131]
	s_mov_b32 m0, s66
	ds_read_b128 v[212:215], v194 offset:16384
	ds_read_b128 v[216:219], v194 offset:17408
	ds_read_b128 v[220:223], v194 offset:18432
	ds_read_b128 v[224:227], v194 offset:19456
	ds_read_b128 v[228:231], v194 offset:20480
	ds_read_b128 v[232:235], v194 offset:21504
	ds_read_b128 v[236:239], v194 offset:22528
	ds_read_b128 v[240:243], v194 offset:23552
	global_load_lds_dwordx4 v[244:245], off
	s_add_i32 m0, s66, 0x2000
	s_add_u32 s66, s38, 0x100000
	v_lshl_add_u64 v[246:247], s[38:39], 0, v[134:135]
	s_addc_u32 s67, s39, 0
	s_add_i32 s68, s60, s43
	global_load_lds_dwordx4 v[246:247], off
	v_lshl_add_u64 v[248:249], s[66:67], 0, v[130:131]
	s_mov_b32 m0, s68
	s_nop 0
	global_load_lds_dwordx4 v[248:249], off
	v_lshl_add_u64 v[248:249], s[66:67], 0, v[134:135]
	s_add_i32 m0, s68, 0x2000
	s_nop 0
	global_load_lds_dwordx4 v[248:249], off
	s_nop 0
	s_waitcnt vmcnt(6)
	s_waitcnt lgkmcnt(0)
	s_barrier
; #define PG8_STAGE(bufoff, gbase, voff) do { _Pragma("unroll") for (int _i = 0; _i < 2; ++_i) \
;         __builtin_amdgcn_global_load_lds((const unsigned*)((const char*)(gbase) + (voff)[_i]), (PG8_LAS unsigned*)(lds + (bufoff) + ldsw + _i * 8192), 16, 0, 0); } while (0)
; #define PG8_LDA(dst, b, h) do { _Pragma("unroll") for (int m = 0; m < 4; ++m) _Pragma("unroll") for (int k = 0; k < 2; ++k) dst[m][k] = *(const PG8_LAS bf16x8*)(lds + PG8_SA(b, h) + aoff + m * 2048 + k * 1024); } while (0)
; #define PG8_LDB(dst, b, h) do { _Pragma("unroll") for (int n = 0; n < 2; ++n) _Pragma("unroll") for (int k = 0; k < 2; ++k) dst[n][k] = *(const PG8_LAS bf16x8*)(lds + PG8_SB(b, h) + boff + n * 2048 + k * 1024); } while (0)
; #define PG8_MMA(ai, bj, At, Bt) do { __builtin_amdgcn_s_setprio(1); _Pragma("unroll") for (int m = 0; m < 4; ++m) _Pragma("unroll") for (int n = 0; n < 2; ++n) _Pragma("unroll") for (int k = 0; k < 2; ++k) \
;         acc[ai][bj][m][n] = __builtin_amdgcn_mfma_f32_16x16x32_bf16(Bt[n][k], At[m][k], acc[ai][bj][m][n], 0, 0, 0); __builtin_amdgcn_s_setprio(0); } while (0)
; #define PG8_WAIT_V(n) asm volatile("s_waitcnt vmcnt(" #n ")" ::: "memory")
; #define PG8_WAIT_L(n) asm volatile("s_waitcnt lgkmcnt(" #n ")" ::: "memory")
; #define PG8_BAR __builtin_amdgcn_s_barrier()
; #define PG8_SCHED __builtin_amdgcn_sched_barrier(0)
; template <class Epi, class Sched, bool ALIGN_EPI = false, bool SP2 = false>
; __device__ __forceinline__ void gemm_phase(PG8_LAS unsigned char* lds, const Gemm g, const Sched& S, const Epi& E) {
;     ...
;             PG8_WAIT_V(8); PG8_WAIT_L(0); PG8_BAR; PG8_MMA(0, 0, At, B0); PG8_MMA(0, 1, At, B1); PG8_BAR; PG8_SCHED;
;             PG8_LDA(At, 0, 1); PG8_STAGE(PG8_SB(0, 0), b2, voffB); PG8_STAGE(PG8_SB(0, 1), b2 + hstep, voffB); PG8_STAGE(PG8_SA(0, 0), a2, voffA);
;             PG8_WAIT_V(8); PG8_WAIT_L(0); PG8_BAR; PG8_MMA(1, 0, At, B0); PG8_MMA(1, 1, At, B1); PG8_BAR; PG8_SCHED;
;             PG8_LDB(B0, 1, 0); PG8_LDB(B1, 1, 1); PG8_SCHED; PG8_LDA(At, 1, 0); PG8_STAGE(PG8_SA(0, 1), a2 + hstep, voffA);
;             PG8_WAIT_V(8); PG8_WAIT_L(0); PG8_BAR; PG8_MMA(0, 0, At, B0); PG8_MMA(0, 1, At, B1); PG8_BAR; PG8_SCHED;
	s_setprio 1
	s_waitcnt lgkmcnt(0)
	v_mfma_f32_16x16x32_bf16 v[60:63], v[144:147], v[212:215], v[60:63]
	v_mfma_f32_16x16x32_bf16 v[56:59], v[152:155], v[212:215], v[56:59]
	v_mfma_f32_16x16x32_bf16 v[44:47], v[144:147], v[220:223], v[44:47]
	v_mfma_f32_16x16x32_bf16 v[40:43], v[152:155], v[220:223], v[40:43]
	v_mfma_f32_16x16x32_bf16 v[28:31], v[144:147], v[228:231], v[28:31]
	v_mfma_f32_16x16x32_bf16 v[24:27], v[152:155], v[228:231], v[24:27]
	v_mfma_f32_16x16x32_bf16 v[12:15], v[144:147], v[236:239], v[12:15]
	v_mfma_f32_16x16x32_bf16 v[8:11], v[152:155], v[236:239], v[8:11]
	v_mfma_f32_16x16x32_bf16 v[60:63], v[148:151], v[216:219], v[60:63]
	v_mfma_f32_16x16x32_bf16 v[56:59], v[156:159], v[216:219], v[56:59]
	v_mfma_f32_16x16x32_bf16 v[44:47], v[148:151], v[224:227], v[44:47]
	v_mfma_f32_16x16x32_bf16 v[40:43], v[156:159], v[224:227], v[40:43]
	v_mfma_f32_16x16x32_bf16 v[28:31], v[148:151], v[232:235], v[28:31]
	v_mfma_f32_16x16x32_bf16 v[24:27], v[156:159], v[232:235], v[24:27]
	v_mfma_f32_16x16x32_bf16 v[12:15], v[148:151], v[240:243], v[12:15]
	v_mfma_f32_16x16x32_bf16 v[8:11], v[156:159], v[240:243], v[8:11]
	s_setprio 0
	s_setprio 1
	v_mfma_f32_16x16x32_bf16 v[52:55], v[160:163], v[212:215], v[52:55]
	v_mfma_f32_16x16x32_bf16 v[48:51], v[168:171], v[212:215], v[48:51]
	v_mfma_f32_16x16x32_bf16 v[36:39], v[160:163], v[220:223], v[36:39]
	v_mfma_f32_16x16x32_bf16 v[32:35], v[168:171], v[220:223], v[32:35]
	v_mfma_f32_16x16x32_bf16 v[20:23], v[160:163], v[228:231], v[20:23]
	v_mfma_f32_16x16x32_bf16 v[16:19], v[168:171], v[228:231], v[16:19]
	v_mfma_f32_16x16x32_bf16 v[4:7], v[160:163], v[236:239], v[4:7]
	v_mfma_f32_16x16x32_bf16 v[0:3], v[168:171], v[236:239], v[0:3]
	v_mfma_f32_16x16x32_bf16 v[52:55], v[164:167], v[216:219], v[52:55]
	v_mfma_f32_16x16x32_bf16 v[48:51], v[208:211], v[216:219], v[48:51]
	v_mfma_f32_16x16x32_bf16 v[36:39], v[164:167], v[224:227], v[36:39]
	v_mfma_f32_16x16x32_bf16 v[32:35], v[208:211], v[224:227], v[32:35]
	v_mfma_f32_16x16x32_bf16 v[20:23], v[164:167], v[232:235], v[20:23]
	v_mfma_f32_16x16x32_bf16 v[16:19], v[208:211], v[232:235], v[16:19]
	v_mfma_f32_16x16x32_bf16 v[4:7], v[164:167], v[240:243], v[4:7]
	v_mfma_f32_16x16x32_bf16 v[0:3], v[208:211], v[240:243], v[0:3]
	s_setprio 0
	s_barrier
	s_add_i32 s66, 0, 0x18000
	s_add_i32 s67, 0, 0x1c000
	v_add_u32_e32 v156, s66, v173
	v_add_u32_e32 v208, s67, v173
	ds_read_b128 v[144:147], v156
	ds_read_b128 v[148:151], v156 offset:1024
	ds_read_b128 v[152:155], v156 offset:2048
	ds_read_b128 v[156:159], v156 offset:3072
	ds_read_b128 v[160:163], v208
	ds_read_b128 v[164:167], v208 offset:1024
	ds_read_b128 v[168:171], v208 offset:2048
	ds_read_b128 v[208:211], v208 offset:3072
	v_lshl_add_u64 v[250:251], s[40:41], 0, v[132:133]
	v_lshl_add_u64 v[248:249], s[40:41], 0, v[128:129]
	s_mov_b32 m0, s44
	s_nop 0
	global_load_lds_dwordx4 v[248:249], off
	s_mov_b32 m0, s45
	s_nop 0
	global_load_lds_dwordx4 v[250:251], off
	s_add_u32 s40, s40, 0x100000
	s_addc_u32 s41, s41, 0
	s_mov_b32 m0, s46
	v_lshl_add_u64 v[252:253], s[40:41], 0, v[128:129]
	ds_read_b128 v[212:215], v194 offset:32768
	ds_read_b128 v[216:219], v194 offset:33792
	ds_read_b128 v[220:223], v194 offset:34816
	ds_read_b128 v[224:227], v194 offset:35840
	ds_read_b128 v[228:231], v194 offset:36864
	ds_read_b128 v[232:235], v194 offset:37888
	ds_read_b128 v[236:239], v194 offset:38912
	ds_read_b128 v[240:243], v194 offset:39936
	global_load_lds_dwordx4 v[252:253], off
	v_lshl_add_u64 v[252:253], s[40:41], 0, v[132:133]
	s_mov_b32 m0, s47
	s_nop 0
	global_load_lds_dwordx4 v[252:253], off
	s_waitcnt vmcnt(8)
	s_waitcnt lgkmcnt(0)
	s_barrier
	s_setprio 1
	s_waitcnt lgkmcnt(0)
	v_mfma_f32_16x16x32_bf16 v[124:127], v[144:147], v[212:215], v[124:127]
	v_mfma_f32_16x16x32_bf16 v[120:123], v[152:155], v[212:215], v[120:123]
	v_mfma_f32_16x16x32_bf16 v[108:111], v[144:147], v[220:223], v[108:111]
	v_mfma_f32_16x16x32_bf16 v[104:107], v[152:155], v[220:223], v[104:107]
	v_mfma_f32_16x16x32_bf16 v[92:95], v[144:147], v[228:231], v[92:95]
	v_mfma_f32_16x16x32_bf16 v[88:91], v[152:155], v[228:231], v[88:91]
	v_mfma_f32_16x16x32_bf16 v[76:79], v[144:147], v[236:239], v[76:79]
	v_mfma_f32_16x16x32_bf16 v[72:75], v[152:155], v[236:239], v[72:75]
	v_mfma_f32_16x16x32_bf16 v[124:127], v[148:151], v[216:219], v[124:127]
	v_mfma_f32_16x16x32_bf16 v[120:123], v[156:159], v[216:219], v[120:123]
	v_mfma_f32_16x16x32_bf16 v[108:111], v[148:151], v[224:227], v[108:111]
	v_mfma_f32_16x16x32_bf16 v[104:107], v[156:159], v[224:227], v[104:107]
	v_mfma_f32_16x16x32_bf16 v[92:95], v[148:151], v[232:235], v[92:95]
	v_mfma_f32_16x16x32_bf16 v[88:91], v[156:159], v[232:235], v[88:91]
	v_mfma_f32_16x16x32_bf16 v[76:79], v[148:151], v[240:243], v[76:79]
	v_mfma_f32_16x16x32_bf16 v[72:75], v[156:159], v[240:243], v[72:75]
	s_setprio 0
	s_setprio 1
	v_mfma_f32_16x16x32_bf16 v[116:119], v[160:163], v[212:215], v[116:119]
	v_mfma_f32_16x16x32_bf16 v[112:115], v[168:171], v[212:215], v[112:115]
	v_mfma_f32_16x16x32_bf16 v[100:103], v[160:163], v[220:223], v[100:103]
	v_mfma_f32_16x16x32_bf16 v[96:99], v[168:171], v[220:223], v[96:99]
	v_mfma_f32_16x16x32_bf16 v[84:87], v[160:163], v[228:231], v[84:87]
	v_mfma_f32_16x16x32_bf16 v[80:83], v[168:171], v[228:231], v[80:83]
	v_mfma_f32_16x16x32_bf16 v[68:71], v[160:163], v[236:239], v[68:71]
	v_mfma_f32_16x16x32_bf16 v[64:67], v[168:171], v[236:239], v[64:67]
	v_mfma_f32_16x16x32_bf16 v[116:119], v[164:167], v[216:219], v[116:119]
	v_mfma_f32_16x16x32_bf16 v[112:115], v[208:211], v[216:219], v[112:115]
	v_mfma_f32_16x16x32_bf16 v[100:103], v[164:167], v[224:227], v[100:103]
	v_mfma_f32_16x16x32_bf16 v[96:99], v[208:211], v[224:227], v[96:99]
	v_mfma_f32_16x16x32_bf16 v[84:87], v[164:167], v[232:235], v[84:87]
	v_mfma_f32_16x16x32_bf16 v[80:83], v[208:211], v[232:235], v[80:83]
	v_mfma_f32_16x16x32_bf16 v[68:71], v[164:167], v[240:243], v[68:71]
	v_mfma_f32_16x16x32_bf16 v[64:67], v[208:211], v[240:243], v[64:67]
	s_setprio 0
	s_barrier
; #define PG8_STAGE(bufoff, gbase, voff) do { _Pragma("unroll") for (int _i = 0; _i < 2; ++_i) \
;         __builtin_amdgcn_global_load_lds((const unsigned*)((const char*)(gbase) + (voff)[_i]), (PG8_LAS unsigned*)(lds + (bufoff) + ldsw + _i * 8192), 16, 0, 0); } while (0)
; #define PG8_LDA(dst, b, h) do { _Pragma("unroll") for (int m = 0; m < 4; ++m) _Pragma("unroll") for (int k = 0; k < 2; ++k) dst[m][k] = *(const PG8_LAS bf16x8*)(lds + PG8_SA(b, h) + aoff + m * 2048 + k * 1024); } while (0)
; #define PG8_MMA(ai, bj, At, Bt) do { __builtin_amdgcn_s_setprio(1); _Pragma("unroll") for (int m = 0; m < 4; ++m) _Pragma("unroll") for (int n = 0; n < 2; ++n) _Pragma("unroll") for (int k = 0; k < 2; ++k) \
;         acc[ai][bj][m][n] = __builtin_amdgcn_mfma_f32_16x16x32_bf16(Bt[n][k], At[m][k], acc[ai][bj][m][n], 0, 0, 0); __builtin_amdgcn_s_setprio(0); } while (0)
; #define PG8_WAIT_V(n) asm volatile("s_waitcnt vmcnt(" #n ")" ::: "memory")
; #define PG8_WAIT_L(n) asm volatile("s_waitcnt lgkmcnt(" #n ")" ::: "memory")
; #define PG8_BAR __builtin_amdgcn_s_barrier()
; #define PG8_SCHED __builtin_amdgcn_sched_barrier(0)
; template <class Epi, class Sched, bool ALIGN_EPI = false, bool SP2 = false>
; __device__ __forceinline__ void gemm_phase(PG8_LAS unsigned char* lds, const Gemm g, const Sched& S, const Epi& E) {
;     ...
;             PG8_LDA(At, 1, 1); PG8_STAGE(PG8_SB(1, 0), b3, voffB); PG8_STAGE(PG8_SB(1, 1), b3 + hstep, voffB); PG8_STAGE(PG8_SA(1, 0), a3, voffA);
;             PG8_WAIT_V(8); PG8_WAIT_L(0); PG8_BAR; PG8_MMA(1, 0, At, B0); PG8_MMA(1, 1, At, B1); PG8_BAR; PG8_SCHED;
	s_add_i32 s40, s66, s43
	v_lshl_add_u64 v[244:245], v[244:245], 0, s[20:21]
	s_mov_b32 m0, s40
	ds_read_b128 v[212:215], v194 offset:49152
	ds_read_b128 v[216:219], v194 offset:50176
	ds_read_b128 v[220:223], v194 offset:51200
	ds_read_b128 v[224:227], v194 offset:52224
	ds_read_b128 v[228:231], v194 offset:53248
	ds_read_b128 v[232:235], v194 offset:54272
	ds_read_b128 v[236:239], v194 offset:55296
	ds_read_b128 v[240:243], v194 offset:56320
	global_load_lds_dwordx4 v[244:245], off
	s_add_i32 m0, s40, 0x2000
	s_add_u32 s38, s38, 0x100080
	v_lshl_add_u64 v[244:245], v[246:247], 0, s[20:21]
	s_addc_u32 s39, s39, 0
	s_add_i32 s40, s67, s43
	global_load_lds_dwordx4 v[244:245], off
	v_lshl_add_u64 v[244:245], s[38:39], 0, v[130:131]
	s_mov_b32 m0, s40
	s_nop 0
	global_load_lds_dwordx4 v[244:245], off
	v_lshl_add_u64 v[244:245], s[38:39], 0, v[134:135]
	s_add_i32 m0, s40, 0x2000
	s_nop 0
	global_load_lds_dwordx4 v[244:245], off
	v_lshl_add_u64 v[244:245], v[248:249], 0, s[20:21]
	s_mov_b32 m0, s51
	s_nop 0
	global_load_lds_dwordx4 v[244:245], off
	v_lshl_add_u64 v[244:245], v[250:251], 0, s[20:21]
	s_mov_b32 m0, s52
	s_nop 0
	global_load_lds_dwordx4 v[244:245], off
	s_waitcnt vmcnt(8)
	s_waitcnt lgkmcnt(0)
	s_barrier
	s_setprio 1
	s_waitcnt lgkmcnt(0)
	v_mfma_f32_16x16x32_bf16 v[60:63], v[144:147], v[212:215], v[60:63]
	v_mfma_f32_16x16x32_bf16 v[56:59], v[152:155], v[212:215], v[56:59]
	v_mfma_f32_16x16x32_bf16 v[44:47], v[144:147], v[220:223], v[44:47]
	v_mfma_f32_16x16x32_bf16 v[40:43], v[152:155], v[220:223], v[40:43]
	v_mfma_f32_16x16x32_bf16 v[28:31], v[144:147], v[228:231], v[28:31]
	v_mfma_f32_16x16x32_bf16 v[24:27], v[152:155], v[228:231], v[24:27]
	v_mfma_f32_16x16x32_bf16 v[12:15], v[144:147], v[236:239], v[12:15]
	v_mfma_f32_16x16x32_bf16 v[8:11], v[152:155], v[236:239], v[8:11]
	v_mfma_f32_16x16x32_bf16 v[60:63], v[148:151], v[216:219], v[60:63]
	v_mfma_f32_16x16x32_bf16 v[56:59], v[156:159], v[216:219], v[56:59]
	v_mfma_f32_16x16x32_bf16 v[44:47], v[148:151], v[224:227], v[44:47]
	v_mfma_f32_16x16x32_bf16 v[40:43], v[156:159], v[224:227], v[40:43]
	v_mfma_f32_16x16x32_bf16 v[28:31], v[148:151], v[232:235], v[28:31]
	v_mfma_f32_16x16x32_bf16 v[24:27], v[156:159], v[232:235], v[24:27]
	v_mfma_f32_16x16x32_bf16 v[12:15], v[148:151], v[240:243], v[12:15]
	v_mfma_f32_16x16x32_bf16 v[8:11], v[156:159], v[240:243], v[8:11]
	s_setprio 0
	s_setprio 1
	v_mfma_f32_16x16x32_bf16 v[52:55], v[160:163], v[212:215], v[52:55]
	v_mfma_f32_16x16x32_bf16 v[48:51], v[168:171], v[212:215], v[48:51]
	v_mfma_f32_16x16x32_bf16 v[36:39], v[160:163], v[220:223], v[36:39]
	v_mfma_f32_16x16x32_bf16 v[32:35], v[168:171], v[220:223], v[32:35]
	v_mfma_f32_16x16x32_bf16 v[20:23], v[160:163], v[228:231], v[20:23]
	v_mfma_f32_16x16x32_bf16 v[16:19], v[168:171], v[228:231], v[16:19]
	v_mfma_f32_16x16x32_bf16 v[4:7], v[160:163], v[236:239], v[4:7]
	v_mfma_f32_16x16x32_bf16 v[0:3], v[168:171], v[236:239], v[0:3]
	v_mfma_f32_16x16x32_bf16 v[52:55], v[164:167], v[216:219], v[52:55]
	v_mfma_f32_16x16x32_bf16 v[48:51], v[208:211], v[216:219], v[48:51]
	v_mfma_f32_16x16x32_bf16 v[36:39], v[164:167], v[224:227], v[36:39]
	v_mfma_f32_16x16x32_bf16 v[32:35], v[208:211], v[224:227], v[32:35]
	v_mfma_f32_16x16x32_bf16 v[20:23], v[164:167], v[232:235], v[20:23]
	v_mfma_f32_16x16x32_bf16 v[16:19], v[208:211], v[232:235], v[16:19]
	v_mfma_f32_16x16x32_bf16 v[4:7], v[164:167], v[240:243], v[4:7]
	v_mfma_f32_16x16x32_bf16 v[0:3], v[208:211], v[240:243], v[0:3]
	s_setprio 0
	s_barrier
	s_add_i32 s65, s65, 2
	s_add_u32 s36, s36, 0x100
	s_addc_u32 s37, s37, 0
	s_add_u32 s63, s63, 0x100
	s_addc_u32 s64, s64, 0
	s_cmp_gt_u32 s65, 61
	s_cbranch_scc0 .LBB0_642
	s_and_b64 vcc, exec, s[22:23]
	s_cbranch_vccz .LBB0_645
	s_barrier
